# prep LoRA-g: gate-weight fragment loads prefetched 3-deep with counted waits
# speedup vs baseline: 1.0021x; 1.0021x over previous
.LBB0_910:
	s_or_b64 exec, exec, s[46:47]
	v_add_u32_e32 v72, v111, v226
	v_ashrrev_i32_e32 v73, 31, v72
	v_lshrrev_b32_e32 v73, 26, v73
	v_add_u32_e32 v72, v72, v73
	v_ashrrev_i32_e32 v72, 6, v72
	v_cvt_pk_bf16_f32 v86, v66, v67
	v_lshl_add_u32 v66, v72, 3, s52
	v_cvt_pk_bf16_f32 v80, v80, v81
	v_cvt_pk_bf16_f32 v84, v82, v83
	v_cvt_pk_bf16_f32 v81, v78, v79
	v_cvt_pk_bf16_f32 v82, v76, v77
	v_cvt_pk_bf16_f32 v83, v74, v75
	v_ashrrev_i32_e32 v67, 31, v66
	v_cvt_pk_bf16_f32 v85, v70, v71
	v_cvt_pk_bf16_f32 v87, v68, v69
	ds_write_b128 v221, v[80:83]
	ds_write_b128 v221, v[84:87] offset:16
	s_waitcnt lgkmcnt(0)
	s_barrier
	v_lshlrev_b64 v[126:127], 11, v[66:67]
	ds_read_b128 v[66:69], v224
	ds_read_b128 v[82:85], v224 offset:64
	s_waitcnt lgkmcnt(1)
	v_mfma_f32_16x16x32_bf16 v[70:73], v[44:47], v[66:69], 0
	v_add_u32_e32 v132, v218, v225
	v_ashrrev_i32_e32 v133, 31, v132
	s_mov_b64 s[6:7], 0x7800400
	v_mfma_f32_16x16x32_bf16 v[74:77], v[50:53], v[66:69], 0
	v_or_b32_e32 v128, v227, v218
	v_ashrrev_i32_e32 v129, 31, v128
	v_cmp_lt_i32_e32 vcc, 0, v128
	v_mfma_f32_16x16x32_bf16 v[78:81], v[54:57], v[66:69], 0
	s_nop 0
	v_cndmask_b32_e64 v201, 0, -1, vcc
	v_cndmask_b32_e32 v200, 0, v210, vcc
	v_mfma_f32_16x16x32_bf16 v[66:69], v[58:61], v[66:69], 0
	v_cndmask_b32_e64 v176, 0, 1.0, vcc
	s_waitcnt lgkmcnt(0)
	v_mfma_f32_16x16x32_bf16 v[70:73], v[32:35], v[82:85], v[70:73]
	v_mfma_f32_16x16x32_bf16 v[74:77], v[36:39], v[82:85], v[74:77]
	v_mfma_f32_16x16x32_bf16 v[78:81], v[40:43], v[82:85], v[78:81]
	v_mfma_f32_16x16x32_bf16 v[66:69], v[62:65], v[82:85], v[66:69]
	ds_read_b128 v[82:85], v222 offset:45056
	ds_read_b128 v[86:89], v222 offset:45072
	s_waitcnt lgkmcnt(1)
	s_nop 1
	v_add_f32_e32 v70, v70, v82
	v_add_f32_e32 v71, v71, v83
	v_mul_f32_e32 v70, 0xbfb8aa3b, v70
	v_mul_f32_e32 v71, 0xbfb8aa3b, v71
	v_exp_f32_e32 v70, v70
	v_exp_f32_e32 v71, v71
	v_add_f32_e32 v70, 1.0, v70
	v_add_f32_e32 v71, 1.0, v71
	v_rcp_f32_e32 v70, v70
	v_rcp_f32_e32 v71, v71
	s_nop 0
	v_pk_mul_f32 v[160:161], v[70:71], s[72:73] op_sel_hi:[1,0]
	v_add_f32_e32 v70, v72, v84
	v_add_f32_e32 v71, v73, v85
	v_mul_f32_e32 v70, 0xbfb8aa3b, v70
	v_mul_f32_e32 v71, 0xbfb8aa3b, v71
	v_exp_f32_e32 v70, v70
	v_exp_f32_e32 v71, v71
	ds_read_b128 v[82:85], v224 offset:192
	v_add_f32_e32 v70, 1.0, v70
	v_add_f32_e32 v71, 1.0, v71
	v_rcp_f32_e32 v70, v70
	v_rcp_f32_e32 v71, v71
	s_nop 0
	v_pk_mul_f32 v[162:163], v[70:71], s[72:73] op_sel_hi:[1,0]
	s_waitcnt lgkmcnt(1)
	v_add_f32_e32 v70, v74, v86
	v_add_f32_e32 v71, v75, v87
	v_mul_f32_e32 v70, 0xbfb8aa3b, v70
	v_mul_f32_e32 v71, 0xbfb8aa3b, v71
	v_exp_f32_e32 v70, v70
	v_exp_f32_e32 v71, v71
	v_add_f32_e32 v70, 1.0, v70
	v_add_f32_e32 v71, 1.0, v71
	v_rcp_f32_e32 v70, v70
	v_rcp_f32_e32 v71, v71
	s_nop 0
	v_pk_mul_f32 v[164:165], v[70:71], s[72:73] op_sel_hi:[1,0]
	v_add_f32_e32 v70, v76, v88
	v_add_f32_e32 v71, v77, v89
	v_mul_f32_e32 v70, 0xbfb8aa3b, v70
	v_mul_f32_e32 v71, 0xbfb8aa3b, v71
	v_exp_f32_e32 v70, v70
	v_exp_f32_e32 v71, v71
	global_load_dwordx4 v[86:89], v[112:113], off offset:64
	v_add_f32_e32 v70, 1.0, v70
	v_add_f32_e32 v71, 1.0, v71
	v_rcp_f32_e32 v70, v70
	v_rcp_f32_e32 v71, v71
	s_nop 0
	v_pk_mul_f32 v[166:167], v[70:71], s[72:73] op_sel_hi:[1,0]
	ds_read_b128 v[70:73], v222 offset:45184
	s_waitcnt lgkmcnt(0)
	v_add_f32_e32 v70, v78, v70
	v_add_f32_e32 v71, v79, v71
	v_mul_f32_e32 v70, 0xbfb8aa3b, v70
	v_mul_f32_e32 v71, 0xbfb8aa3b, v71
	v_exp_f32_e32 v70, v70
	v_exp_f32_e32 v71, v71
	v_add_f32_e32 v70, 1.0, v70
	v_add_f32_e32 v71, 1.0, v71
	v_rcp_f32_e32 v70, v70
	v_rcp_f32_e32 v71, v71
	s_nop 0
	v_pk_mul_f32 v[150:151], v[70:71], s[72:73] op_sel_hi:[1,0]
	v_add_f32_e32 v70, v80, v72
	v_add_f32_e32 v71, v81, v73
	v_mul_f32_e32 v70, 0xbfb8aa3b, v70
	v_mul_f32_e32 v71, 0xbfb8aa3b, v71
	v_exp_f32_e32 v70, v70
	v_exp_f32_e32 v71, v71
	v_add_f32_e32 v70, 1.0, v70
	v_add_f32_e32 v71, 1.0, v71
	v_rcp_f32_e32 v70, v70
	v_rcp_f32_e32 v71, v71
	s_nop 0
	v_pk_mul_f32 v[152:153], v[70:71], s[72:73] op_sel_hi:[1,0]
	ds_read_b128 v[70:73], v222 offset:45200
	s_waitcnt lgkmcnt(0)
	v_add_f32_e32 v66, v66, v70
	v_add_f32_e32 v67, v67, v71
	v_mul_f32_e32 v66, 0xbfb8aa3b, v66
	v_mul_f32_e32 v67, 0xbfb8aa3b, v67
	v_exp_f32_e32 v66, v66
	v_exp_f32_e32 v67, v67
	v_add_f32_e32 v66, 1.0, v66
	v_add_f32_e32 v67, 1.0, v67
	v_rcp_f32_e32 v66, v66
	v_rcp_f32_e32 v67, v67
	s_nop 0
	v_pk_mul_f32 v[156:157], v[66:67], s[72:73] op_sel_hi:[1,0]
	v_add_f32_e32 v66, v68, v72
	v_add_f32_e32 v67, v69, v73
	v_mul_f32_e32 v66, 0xbfb8aa3b, v66
	v_mul_f32_e32 v67, 0xbfb8aa3b, v67
	v_exp_f32_e32 v66, v66
	v_exp_f32_e32 v67, v67
	v_add_f32_e32 v66, 1.0, v66
	v_add_f32_e32 v67, 1.0, v67
	v_rcp_f32_e32 v66, v66
	v_rcp_f32_e32 v67, v67
	s_nop 0
	v_pk_mul_f32 v[158:159], v[66:67], s[72:73] op_sel_hi:[1,0]
	ds_read_b128 v[66:69], v224 offset:128
	s_waitcnt lgkmcnt(0)
	v_mfma_f32_16x16x32_bf16 v[70:73], v[0:3], v[66:69], 0
	v_mfma_f32_16x16x32_bf16 v[74:77], v[4:7], v[66:69], 0
	v_mfma_f32_16x16x32_bf16 v[78:81], v[8:11], v[66:69], 0
	v_mfma_f32_16x16x32_bf16 v[66:69], v[12:15], v[66:69], 0
	v_mfma_f32_16x16x32_bf16 v[70:73], v[16:19], v[82:85], v[70:73]
	v_mfma_f32_16x16x32_bf16 v[74:77], v[20:23], v[82:85], v[74:77]
	v_mfma_f32_16x16x32_bf16 v[78:81], v[24:27], v[82:85], v[78:81]
	v_mfma_f32_16x16x32_bf16 v[66:69], v[28:31], v[82:85], v[66:69]
	ds_read_b128 v[82:85], v222 offset:47104
	s_waitcnt lgkmcnt(0)
	s_nop 2
	v_add_f32_e32 v70, v70, v82
	v_mul_f32_e32 v70, 0xbfb8aa3b, v70
	v_exp_f32_e32 v70, v70
	s_nop 0
	v_add_f32_e32 v70, 1.0, v70
	v_rcp_f32_e32 v146, v70
	v_add_f32_e32 v70, v71, v83
	v_mul_f32_e32 v70, 0xbfb8aa3b, v70
	v_exp_f32_e32 v70, v70
	s_nop 0
	v_add_f32_e32 v70, 1.0, v70
	v_rcp_f32_e32 v147, v70
	v_add_f32_e32 v70, v72, v84
	v_mul_f32_e32 v70, 0xbfb8aa3b, v70
	v_exp_f32_e32 v70, v70
	s_nop 0
	v_add_f32_e32 v70, 1.0, v70
	v_rcp_f32_e32 v148, v70
	v_add_f32_e32 v70, v73, v85
	v_mul_f32_e32 v70, 0xbfb8aa3b, v70
	v_exp_f32_e32 v70, v70
	global_load_dwordx4 v[82:85], v[118:119], off
	v_add_f32_e32 v70, 1.0, v70
	v_rcp_f32_e32 v149, v70
	ds_read_b128 v[70:73], v222 offset:47120
	s_waitcnt lgkmcnt(0)
	v_add_f32_e32 v70, v74, v70
	v_mul_f32_e32 v70, 0xbfb8aa3b, v70
	v_exp_f32_e32 v70, v70
	s_nop 0
	v_add_f32_e32 v70, 1.0, v70
	v_rcp_f32_e32 v142, v70
	v_add_f32_e32 v70, v75, v71
	v_mul_f32_e32 v70, 0xbfb8aa3b, v70
	v_exp_f32_e32 v70, v70
	s_nop 0
	v_add_f32_e32 v70, 1.0, v70
	v_rcp_f32_e32 v143, v70
	v_add_f32_e32 v70, v76, v72
	v_mul_f32_e32 v70, 0xbfb8aa3b, v70
	v_exp_f32_e32 v70, v70
	s_nop 0
	v_add_f32_e32 v70, 1.0, v70
	v_rcp_f32_e32 v144, v70
	v_add_f32_e32 v70, v77, v73
	v_mul_f32_e32 v70, 0xbfb8aa3b, v70
	v_exp_f32_e32 v70, v70
	global_load_dwordx4 v[74:77], v[114:115], off
	v_add_f32_e32 v70, 1.0, v70
	v_rcp_f32_e32 v145, v70
	ds_read_b128 v[70:73], v222 offset:47232
	s_waitcnt lgkmcnt(0)
	v_add_f32_e32 v70, v78, v70
	v_mul_f32_e32 v70, 0xbfb8aa3b, v70
	v_exp_f32_e32 v70, v70
	s_nop 0
	v_add_f32_e32 v70, 1.0, v70
	v_rcp_f32_e32 v138, v70
	v_add_f32_e32 v70, v79, v71
	v_mul_f32_e32 v70, 0xbfb8aa3b, v70
	v_exp_f32_e32 v70, v70
	s_nop 0
	v_add_f32_e32 v70, 1.0, v70
	v_rcp_f32_e32 v139, v70
	v_add_f32_e32 v70, v80, v72
	v_mul_f32_e32 v70, 0xbfb8aa3b, v70
	v_exp_f32_e32 v70, v70
	s_nop 0
	v_add_f32_e32 v70, 1.0, v70
	v_rcp_f32_e32 v140, v70
	v_add_f32_e32 v70, v81, v73
	v_mul_f32_e32 v70, 0xbfb8aa3b, v70
	v_exp_f32_e32 v70, v70
	global_load_dwordx4 v[78:81], v[116:117], off
	global_load_dwordx4 v[242:245], v[114:115], off offset:64
	global_load_dwordx4 v[246:249], v[116:117], off offset:64
	global_load_dwordx4 v[250:253], v[118:119], off offset:64
	v_add_f32_e32 v70, 1.0, v70
	v_rcp_f32_e32 v141, v70
	ds_read_b128 v[70:73], v222 offset:47248
	s_waitcnt lgkmcnt(0)
	v_add_f32_e32 v66, v66, v70
	v_mul_f32_e32 v66, 0xbfb8aa3b, v66
	v_exp_f32_e32 v66, v66
	s_nop 0
	v_add_f32_e32 v66, 1.0, v66
	v_rcp_f32_e32 v134, v66
	v_add_f32_e32 v66, v67, v71
	v_mul_f32_e32 v66, 0xbfb8aa3b, v66
	v_exp_f32_e32 v66, v66
	s_nop 0
	v_add_f32_e32 v66, 1.0, v66
	v_rcp_f32_e32 v135, v66
	v_add_f32_e32 v66, v68, v72
	v_mul_f32_e32 v66, 0xbfb8aa3b, v66
	v_exp_f32_e32 v66, v66
	s_nop 0
	v_add_f32_e32 v66, 1.0, v66
	v_rcp_f32_e32 v136, v66
	v_add_f32_e32 v66, v69, v73
	global_load_dwordx4 v[70:73], v[112:113], off
	v_mul_f32_e32 v66, 0xbfb8aa3b, v66
	v_exp_f32_e32 v66, v66
	s_nop 0
	v_add_f32_e32 v66, 1.0, v66
	v_rcp_f32_e32 v137, v66
	ds_read_b128 v[66:69], v224 offset:256
	s_waitcnt vmcnt(0) lgkmcnt(0)
	v_mfma_f32_16x16x32_bf16 v[70:73], v[70:73], v[66:69], 0
	v_mfma_f32_16x16x32_bf16 v[74:77], v[74:77], v[66:69], 0
	v_mfma_f32_16x16x32_bf16 v[78:81], v[78:81], v[66:69], 0
	v_mfma_f32_16x16x32_bf16 v[66:69], v[82:85], v[66:69], 0
	ds_read_b128 v[82:85], v224 offset:320
	s_waitcnt lgkmcnt(0)
	v_mfma_f32_16x16x32_bf16 v[70:73], v[86:89], v[82:85], v[70:73]
	global_load_dwordx4 v[86:89], v[112:113], off offset:128
	v_mfma_f32_16x16x32_bf16 v[74:77], v[242:245], v[82:85], v[74:77]
	global_load_dwordx4 v[242:245], v[114:115], off offset:128
	v_mfma_f32_16x16x32_bf16 v[78:81], v[246:249], v[82:85], v[78:81]
	global_load_dwordx4 v[246:249], v[116:117], off offset:128
	v_mfma_f32_16x16x32_bf16 v[66:69], v[250:253], v[82:85], v[66:69]
	global_load_dwordx4 v[250:253], v[118:119], off offset:128
	ds_read_b128 v[82:85], v224 offset:384
	s_waitcnt vmcnt(3) lgkmcnt(0)
	v_mfma_f32_16x16x32_bf16 v[86:89], v[86:89], v[82:85], v[70:73]
	s_waitcnt vmcnt(2)
	v_mfma_f32_16x16x32_bf16 v[90:93], v[242:245], v[82:85], v[74:77]
	s_nop 2
	global_load_dwordx4 v[74:77], v[112:113], off offset:192
	global_load_dwordx4 v[242:245], v[116:117], off offset:192
	s_waitcnt vmcnt(3)
	v_mfma_f32_16x16x32_bf16 v[168:171], v[246:249], v[82:85], v[78:81]
	s_nop 2
	global_load_dwordx4 v[78:81], v[114:115], off offset:192
	global_load_dwordx4 v[246:249], v[118:119], off offset:192
	s_waitcnt vmcnt(4)
	v_mfma_f32_16x16x32_bf16 v[66:69], v[250:253], v[82:85], v[66:69]
	ds_read_b128 v[70:73], v224 offset:448
	s_waitcnt vmcnt(3) lgkmcnt(0)
	v_mfma_f32_16x16x32_bf16 v[74:77], v[74:77], v[70:73], v[86:89]
	s_waitcnt vmcnt(1)
	v_mfma_f32_16x16x32_bf16 v[78:81], v[78:81], v[70:73], v[90:93]
	v_mfma_f32_16x16x32_bf16 v[82:85], v[242:245], v[70:73], v[168:171]
	s_waitcnt vmcnt(0)
	v_mfma_f32_16x16x32_bf16 v[66:69], v[246:249], v[70:73], v[66:69]
	v_lshlrev_b64 v[70:71], 11, v[132:133]
	v_lshl_add_u64 v[70:71], s[2:3], 0, v[70:71]
	v_lshl_add_u64 v[70:71], s[56:57], 1, v[70:71]
	v_lshl_add_u64 v[86:87], v[70:71], 0, v[48:49]
	v_lshl_add_u64 v[88:89], v[86:87], 0, s[6:7]
	v_cvt_pk_bf16_f32 v72, v78, v79
	s_mov_b64 s[6:7], 0x7800440
	v_cvt_pk_bf16_f32 v70, v74, v75
	v_cvt_pk_bf16_f32 v71, v76, v77
	v_cvt_pk_bf16_f32 v73, v80, v81
	global_store_dwordx4 v[88:89], v[70:73], off
	s_nop 1
	v_cvt_pk_bf16_f32 v72, v66, v67
	v_lshl_add_u64 v[66:67], v[86:87], 0, s[6:7]
	v_cvt_pk_bf16_f32 v70, v82, v83
	v_cvt_pk_bf16_f32 v71, v84, v85
	v_cvt_pk_bf16_f32 v73, v68, v69
	global_store_dwordx4 v[66:67], v[70:73], off
	s_nop 1
	v_lshl_add_u64 v[66:67], v[126:127], 0, v[128:129]
	v_mov_b64_e32 v[68:69], s[54:55]
	v_mad_u64_u32 v[182:183], s[6:7], v66, s95, v[68:69]
	v_mad_i32_i24 v183, v67, s95, v183
	v_mov_b64_e32 v[66:67], s[12:13]
	v_mad_i64_i32 v[202:203], s[6:7], v132, s19, v[66:67]
	v_lshl_add_u64 v[78:79], v[120:121], 1, v[202:203]
	s_mov_b64 s[6:7], 0x800
	v_lshl_add_u64 v[74:75], v[78:79], 0, s[6:7]
	v_lshl_add_u64 v[82:83], v[78:79], 0, v[200:201]
	global_load_dwordx4 v[70:73], v[78:79], off offset:2048
	global_load_dwordx4 v[66:69], v[78:79], off offset:3072
	s_nop 0
	global_load_dwordx4 v[74:77], v[74:75], off offset:2048
	v_lshl_add_u64 v[86:87], v[82:83], 0, s[6:7]
	global_load_dwordx4 v[78:81], v[82:83], off offset:2048
	s_nop 0
	global_load_dwordx4 v[82:85], v[82:83], off offset:3072
	s_nop 0
	global_load_dwordx4 v[86:89], v[86:87], off offset:2048
	ds_read_b128 v[170:173], v223 offset:32768
	ds_read_b128 v[90:93], v223 offset:32784
	ds_read_b128 v[178:181], v223 offset:34816
	ds_read_b128 v[184:187], v223 offset:36864
	v_lshl_add_u64 v[182:183], v[182:183], 0, v[48:49]
	s_mov_b64 s[6:7], 0x280
	s_waitcnt vmcnt(5)
	v_lshlrev_b32_e32 v174, 16, v70
	v_and_b32_e32 v175, 0xffff0000, v70
	v_lshlrev_b32_e32 v70, 16, v71
	v_and_b32_e32 v71, 0xffff0000, v71
	s_waitcnt vmcnt(2)
	v_lshlrev_b32_e32 v168, 16, v78
	v_and_b32_e32 v169, 0xffff0000, v78
	v_xor_b32_e32 v197, 0x80000000, v175
	v_xor_b32_e32 v196, 0x80000000, v174
	v_lshlrev_b32_e32 v78, 16, v79
	v_and_b32_e32 v79, 0xffff0000, v79
	v_pk_fma_f32 v[196:197], v[176:177], v[168:169], v[196:197] op_sel_hi:[0,1,1]
	v_xor_b32_e32 v169, 0x80000000, v71
	v_xor_b32_e32 v168, 0x80000000, v70
	v_lshlrev_b32_e32 v188, 16, v66
	v_and_b32_e32 v189, 0xffff0000, v66
	v_lshlrev_b32_e32 v66, 16, v67
	v_and_b32_e32 v67, 0xffff0000, v67
	v_pk_fma_f32 v[78:79], v[176:177], v[78:79], v[168:169] op_sel_hi:[0,1,1]
	s_waitcnt vmcnt(1)
	v_lshlrev_b32_e32 v192, 16, v82
	v_and_b32_e32 v193, 0xffff0000, v82
	v_lshlrev_b32_e32 v82, 16, v83
	v_and_b32_e32 v83, 0xffff0000, v83
	s_waitcnt lgkmcnt(3)
	v_pk_fma_f32 v[168:169], v[172:173], v[78:79], v[70:71]
	v_xor_b32_e32 v71, 0x80000000, v189
	v_xor_b32_e32 v70, 0x80000000, v188
	v_xor_b32_e32 v79, 0x80000000, v67
	v_xor_b32_e32 v78, 0x80000000, v66
	v_pk_fma_f32 v[70:71], v[176:177], v[192:193], v[70:71] op_sel_hi:[0,1,1]
	v_pk_fma_f32 v[78:79], v[176:177], v[82:83], v[78:79] op_sel_hi:[0,1,1]
	v_pk_fma_f32 v[170:171], v[170:171], v[196:197], v[174:175]
	s_waitcnt lgkmcnt(1)
	v_pk_fma_f32 v[172:173], v[180:181], v[78:79], v[66:67]
	v_pk_fma_f32 v[174:175], v[178:179], v[70:71], v[188:189]
	ds_read_b128 v[178:181], v223 offset:38912
	v_lshlrev_b32_e32 v190, 16, v74
	v_and_b32_e32 v191, 0xffff0000, v74
	v_lshlrev_b32_e32 v74, 16, v75
	v_and_b32_e32 v75, 0xffff0000, v75
	s_waitcnt vmcnt(0)
	v_lshlrev_b32_e32 v194, 16, v86
	v_and_b32_e32 v195, 0xffff0000, v86
	v_xor_b32_e32 v67, 0x80000000, v191
	v_xor_b32_e32 v66, 0x80000000, v190
	v_lshlrev_b32_e32 v86, 16, v87
	v_and_b32_e32 v87, 0xffff0000, v87
	v_pk_fma_f32 v[70:71], v[176:177], v[194:195], v[66:67] op_sel_hi:[0,1,1]
	v_xor_b32_e32 v67, 0x80000000, v75
	v_xor_b32_e32 v66, 0x80000000, v74
	v_pk_fma_f32 v[66:67], v[176:177], v[86:87], v[66:67] op_sel_hi:[0,1,1]
	s_waitcnt lgkmcnt(0)
	v_pk_mul_f32 v[178:179], v[178:179], v[174:175]
	v_pk_mul_f32 v[180:181], v[180:181], v[172:173]
	v_pk_fma_f32 v[66:67], v[186:187], v[66:67], v[74:75]
	v_pk_mul_f32 v[74:75], v[180:181], v[180:181]
	v_pk_mul_f32 v[78:79], v[178:179], v[178:179]
	v_lshlrev_b32_e32 v86, 16, v72
	v_pk_mov_b32 v[82:83], v[78:79], v[74:75] op_sel:[1,0]
	v_mov_b32_e32 v79, v75
	v_pk_add_f32 v[74:75], v[82:83], v[78:79]
	v_and_b32_e32 v87, 0xffff0000, v72
	v_pk_fma_f32 v[70:71], v[184:185], v[70:71], v[190:191]
	v_pk_add_f32 v[192:193], v[74:75], v[74:75] op_sel_hi:[0,1]
	v_lshlrev_b32_e32 v184, 16, v73
	v_and_b32_e32 v185, 0xffff0000, v73
	v_lshlrev_b32_e32 v190, 16, v68
	v_and_b32_e32 v191, 0xffff0000, v68
	v_lshlrev_b32_e32 v188, 16, v69
	v_and_b32_e32 v189, 0xffff0000, v69
	v_lshlrev_b32_e32 v68, 16, v76
	v_and_b32_e32 v69, 0xffff0000, v76
	v_lshlrev_b32_e32 v72, 16, v77
	v_and_b32_e32 v73, 0xffff0000, v77
	v_lshlrev_b32_e32 v186, 16, v80
	v_and_b32_e32 v187, 0xffff0000, v80
	v_lshlrev_b32_e32 v76, 16, v88
	v_and_b32_e32 v77, 0xffff0000, v88
	v_lshlrev_b32_e32 v74, 16, v89
	v_and_b32_e32 v75, 0xffff0000, v89
	v_xor_b32_e32 v89, 0x80000000, v87
	v_xor_b32_e32 v88, 0x80000000, v86
	v_lshlrev_b32_e32 v194, 16, v81
	v_and_b32_e32 v195, 0xffff0000, v81
	v_lshlrev_b32_e32 v196, 16, v84
	v_and_b32_e32 v197, 0xffff0000, v84
	v_lshlrev_b32_e32 v198, 16, v85
	v_and_b32_e32 v199, 0xffff0000, v85
	ds_read_b128 v[78:81], v223 offset:34832
	ds_read_b128 v[82:85], v223 offset:36880
	v_pk_fma_f32 v[88:89], v[176:177], v[186:187], v[88:89] op_sel_hi:[0,1,1]
	v_xor_b32_e32 v187, 0x80000000, v185
	v_xor_b32_e32 v186, 0x80000000, v184
	v_pk_fma_f32 v[186:187], v[176:177], v[194:195], v[186:187] op_sel_hi:[0,1,1]
	v_pk_fma_f32 v[184:185], v[92:93], v[186:187], v[184:185]
	v_pk_fma_f32 v[186:187], v[90:91], v[88:89], v[86:87]
	v_xor_b32_e32 v87, 0x80000000, v191
	v_xor_b32_e32 v86, 0x80000000, v190
	v_pk_fma_f32 v[86:87], v[176:177], v[196:197], v[86:87] op_sel_hi:[0,1,1]
	s_waitcnt lgkmcnt(1)
	v_pk_fma_f32 v[190:191], v[78:79], v[86:87], v[190:191]
	v_xor_b32_e32 v79, 0x80000000, v69
	v_xor_b32_e32 v78, 0x80000000, v68
	v_pk_fma_f32 v[76:77], v[176:177], v[76:77], v[78:79] op_sel_hi:[0,1,1]
	v_xor_b32_e32 v79, 0x80000000, v73
	v_xor_b32_e32 v78, 0x80000000, v72
	v_pk_fma_f32 v[74:75], v[176:177], v[74:75], v[78:79] op_sel_hi:[0,1,1]
	s_waitcnt lgkmcnt(0)
	v_pk_fma_f32 v[78:79], v[84:85], v[74:75], v[72:73]
	ds_read_b128 v[72:75], v223 offset:38928
	v_xor_b32_e32 v89, 0x80000000, v189
	v_xor_b32_e32 v88, 0x80000000, v188
	v_pk_fma_f32 v[88:89], v[176:177], v[198:199], v[88:89] op_sel_hi:[0,1,1]
	v_pk_fma_f32 v[188:189], v[80:81], v[88:89], v[188:189]
	s_waitcnt lgkmcnt(0)
	v_pk_mul_f32 v[194:195], v[72:73], v[190:191]
	v_pk_mul_f32 v[196:197], v[74:75], v[188:189]
	v_pk_fma_f32 v[76:77], v[82:83], v[76:77], v[68:69]
	v_pk_mul_f32 v[68:69], v[196:197], v[196:197]
	v_pk_mul_f32 v[72:73], v[194:195], v[194:195]
	s_nop 0
	v_pk_mov_b32 v[74:75], v[72:73], v[68:69] op_sel:[1,0]
	v_mov_b32_e32 v73, v69
	v_pk_add_f32 v[68:69], v[74:75], v[72:73]
	v_lshl_add_u64 v[72:73], v[182:183], 0, s[6:7]
	v_pk_add_f32 v[198:199], v[68:69], v[68:69] op_sel_hi:[0,1]
	v_cvt_pk_bf16_f32 v68, v70, v71
	v_cvt_pk_bf16_f32 v69, v66, v67
	v_cvt_pk_bf16_f32 v70, v76, v77
	v_cvt_pk_bf16_f32 v71, v78, v79
	global_store_dwordx4 v[72:73], v[68:71], off
	s_nop 1
	s_mov_b64 s[6:7], 0x200
	v_lshl_add_u64 v[70:71], v[182:183], 0, s[6:7]
	v_cvt_pk_bf16_f32 v66, v170, v171
	v_cvt_pk_bf16_f32 v67, v168, v169
	v_cvt_pk_bf16_f32 v68, v186, v187
	v_cvt_pk_bf16_f32 v69, v184, v185
	global_store_dwordx4 v[70:71], v[66:69], off
	s_nop 1
	v_lshl_add_u64 v[78:79], v[122:123], 1, v[202:203]
	s_mov_b64 s[6:7], 0x840
	v_cvt_pk_bf16_f32 v66, v160, v161
	v_cvt_pk_bf16_f32 v67, v162, v163
	v_cvt_pk_bf16_f32 v68, v164, v165
	v_cvt_pk_bf16_f32 v69, v166, v167
	global_store_dwordx4 v[182:183], v[66:69], off
	s_nop 1
	v_lshl_add_u64 v[74:75], v[78:79], 0, s[6:7]
	v_lshl_add_u64 v[82:83], v[78:79], 0, v[200:201]
	global_load_dwordx4 v[66:69], v[78:79], off offset:2112
	global_load_dwordx4 v[70:73], v[78:79], off offset:3136
	s_nop 0
	global_load_dwordx4 v[74:77], v[74:75], off offset:2048
	v_lshl_add_u64 v[86:87], v[82:83], 0, s[6:7]
	global_load_dwordx4 v[78:81], v[82:83], off offset:2112
	s_nop 0
	global_load_dwordx4 v[82:85], v[82:83], off offset:3136
	s_nop 0
	global_load_dwordx4 v[86:89], v[86:87], off offset:2048
	ds_read_b128 v[160:163], v223 offset:32896
	ds_read_b128 v[90:93], v223 offset:32912
	ds_read_b128 v[164:167], v223 offset:34944
	ds_read_b128 v[200:203], v223 offset:36992
	s_mov_b64 s[6:7], 0x2c0
	s_waitcnt vmcnt(5)
	v_lshlrev_b32_e32 v212, 16, v66
	v_and_b32_e32 v213, 0xffff0000, v66
	v_lshlrev_b32_e32 v66, 16, v67
	v_and_b32_e32 v67, 0xffff0000, v67
	s_waitcnt vmcnt(4)
	v_lshlrev_b32_e32 v214, 16, v70
	v_and_b32_e32 v215, 0xffff0000, v70
	v_lshlrev_b32_e32 v228, 16, v71
	v_and_b32_e32 v229, 0xffff0000, v71
	s_waitcnt vmcnt(2)
	v_lshlrev_b32_e32 v70, 16, v78
	v_and_b32_e32 v71, 0xffff0000, v78
	v_xor_b32_e32 v237, 0x80000000, v213
	v_xor_b32_e32 v236, 0x80000000, v212
	v_lshlrev_b32_e32 v230, 16, v74
	v_and_b32_e32 v231, 0xffff0000, v74
	v_lshlrev_b32_e32 v232, 16, v75
	v_and_b32_e32 v233, 0xffff0000, v75
	v_lshlrev_b32_e32 v74, 16, v79
	v_and_b32_e32 v75, 0xffff0000, v79
	v_pk_fma_f32 v[70:71], v[176:177], v[70:71], v[236:237] op_sel_hi:[0,1,1]
	v_xor_b32_e32 v237, 0x80000000, v67
	v_xor_b32_e32 v236, 0x80000000, v66
	v_pk_fma_f32 v[74:75], v[176:177], v[74:75], v[236:237] op_sel_hi:[0,1,1]
	s_waitcnt vmcnt(1)
	v_lshlrev_b32_e32 v78, 16, v82
	v_and_b32_e32 v79, 0xffff0000, v82
	v_lshlrev_b32_e32 v82, 16, v83
	v_and_b32_e32 v83, 0xffff0000, v83
	s_waitcnt lgkmcnt(3)
	v_pk_fma_f32 v[66:67], v[162:163], v[74:75], v[66:67]
	v_xor_b32_e32 v75, 0x80000000, v229
	v_xor_b32_e32 v74, 0x80000000, v228
	s_waitcnt vmcnt(0)
	v_lshlrev_b32_e32 v234, 16, v86
	v_and_b32_e32 v235, 0xffff0000, v86
	v_lshlrev_b32_e32 v86, 16, v87
	v_and_b32_e32 v87, 0xffff0000, v87
	v_pk_fma_f32 v[70:71], v[160:161], v[70:71], v[212:213]
	v_pk_fma_f32 v[82:83], v[176:177], v[82:83], v[74:75] op_sel_hi:[0,1,1]
	v_xor_b32_e32 v75, 0x80000000, v215
	v_xor_b32_e32 v74, 0x80000000, v214
	v_xor_b32_e32 v161, 0x80000000, v233
	v_xor_b32_e32 v160, 0x80000000, v232
	v_pk_fma_f32 v[74:75], v[176:177], v[78:79], v[74:75] op_sel_hi:[0,1,1]
	v_pk_fma_f32 v[86:87], v[176:177], v[86:87], v[160:161] op_sel_hi:[0,1,1]
	v_lshlrev_b32_e32 v212, 16, v68
	v_and_b32_e32 v213, 0xffff0000, v68
	s_waitcnt lgkmcnt(1)
	v_pk_fma_f32 v[74:75], v[164:165], v[74:75], v[214:215]
	v_pk_fma_f32 v[78:79], v[166:167], v[82:83], v[228:229]
	v_xor_b32_e32 v83, 0x80000000, v231
	v_xor_b32_e32 v82, 0x80000000, v230
	s_waitcnt lgkmcnt(0)
	v_pk_fma_f32 v[160:161], v[202:203], v[86:87], v[232:233]
	v_lshlrev_b32_e32 v68, 16, v69
	v_and_b32_e32 v69, 0xffff0000, v69
	v_lshlrev_b32_e32 v214, 16, v72
	v_and_b32_e32 v215, 0xffff0000, v72
	v_lshlrev_b32_e32 v232, 16, v73
	v_and_b32_e32 v233, 0xffff0000, v73
	v_lshlrev_b32_e32 v72, 16, v80
	v_and_b32_e32 v73, 0xffff0000, v80
	v_xor_b32_e32 v241, 0x80000000, v213
	v_xor_b32_e32 v240, 0x80000000, v212
	v_pk_fma_f32 v[82:83], v[176:177], v[234:235], v[82:83] op_sel_hi:[0,1,1]
	v_lshlrev_b32_e32 v234, 16, v76
	v_and_b32_e32 v235, 0xffff0000, v76
	v_lshlrev_b32_e32 v236, 16, v77
	v_and_b32_e32 v237, 0xffff0000, v77
	v_lshlrev_b32_e32 v76, 16, v81
	v_and_b32_e32 v77, 0xffff0000, v81
	v_pk_fma_f32 v[72:73], v[176:177], v[72:73], v[240:241] op_sel_hi:[0,1,1]
	v_xor_b32_e32 v241, 0x80000000, v69
	v_xor_b32_e32 v240, 0x80000000, v68
	v_pk_fma_f32 v[162:163], v[200:201], v[82:83], v[230:231]
	ds_read_b128 v[164:167], v223 offset:39040
	ds_read_b128 v[200:203], v223 offset:34960
	ds_read_b128 v[228:231], v223 offset:37008
	v_pk_fma_f32 v[76:77], v[176:177], v[76:77], v[240:241] op_sel_hi:[0,1,1]
	v_lshlrev_b32_e32 v80, 16, v84
	v_and_b32_e32 v81, 0xffff0000, v84
	v_lshlrev_b32_e32 v84, 16, v85
	v_and_b32_e32 v85, 0xffff0000, v85
	v_pk_fma_f32 v[68:69], v[92:93], v[76:77], v[68:69]
	v_xor_b32_e32 v77, 0x80000000, v233
	v_xor_b32_e32 v76, 0x80000000, v232
	v_pk_fma_f32 v[84:85], v[176:177], v[84:85], v[76:77] op_sel_hi:[0,1,1]
	v_xor_b32_e32 v77, 0x80000000, v215
	v_xor_b32_e32 v76, 0x80000000, v214
	v_pk_fma_f32 v[76:77], v[176:177], v[80:81], v[76:77] op_sel_hi:[0,1,1]
	s_waitcnt lgkmcnt(1)
	v_pk_fma_f32 v[76:77], v[200:201], v[76:77], v[214:215]
	v_pk_fma_f32 v[80:81], v[202:203], v[84:85], v[232:233]
	ds_read_b128 v[200:203], v223 offset:39056
	v_pk_mul_f32 v[86:87], v[164:165], v[74:75]
	v_pk_mul_f32 v[82:83], v[166:167], v[78:79]
	v_mul_f32_e32 v164, v86, v86
	v_pk_fma_f32 v[164:165], v[86:87], v[86:87], v[164:165] op_sel_hi:[1,1,0]
	v_lshlrev_b32_e32 v238, 16, v88
	v_and_b32_e32 v239, 0xffff0000, v88
	v_lshlrev_b32_e32 v88, 16, v89
	v_and_b32_e32 v89, 0xffff0000, v89
	v_pk_fma_f32 v[72:73], v[90:91], v[72:73], v[212:213]
	v_xor_b32_e32 v85, 0x80000000, v235
	v_xor_b32_e32 v84, 0x80000000, v234
	v_xor_b32_e32 v91, 0x80000000, v237
	v_xor_b32_e32 v90, 0x80000000, v236
	v_mul_f32_e32 v164, v82, v82
	v_pk_fma_f32 v[84:85], v[176:177], v[238:239], v[84:85] op_sel_hi:[0,1,1]
	v_pk_fma_f32 v[88:89], v[176:177], v[88:89], v[90:91] op_sel_hi:[0,1,1]
	v_pk_fma_f32 v[166:167], v[82:83], v[82:83], v[164:165] op_sel_hi:[1,1,0]
	s_waitcnt lgkmcnt(1)
	v_pk_fma_f32 v[90:91], v[230:231], v[88:89], v[236:237]
	v_pk_fma_f32 v[92:93], v[228:229], v[84:85], v[234:235]
	s_waitcnt lgkmcnt(0)
	v_pk_mul_f32 v[84:85], v[202:203], v[80:81]
	v_pk_mul_f32 v[88:89], v[200:201], v[76:77]
	v_mul_f32_e32 v164, v84, v84
	v_mul_f32_e32 v192, v88, v88
	v_mul_f32_e32 v198, v89, v89
	v_mul_f32_e32 v166, v85, v85
	v_pk_add_f32 v[192:193], v[192:193], v[198:199]
	v_pk_add_f32 v[164:165], v[164:165], v[166:167]
	v_lshl_add_u64 v[166:167], v[182:183], 0, s[6:7]
	v_pk_add_f32 v[164:165], v[192:193], v[164:165]
	v_cvt_pk_bf16_f32 v162, v162, v163
	v_add_f32_e32 v129, v164, v165
	v_cvt_pk_bf16_f32 v163, v160, v161
	v_cvt_pk_bf16_f32 v164, v92, v93
	v_cvt_pk_bf16_f32 v165, v90, v91
	global_store_dwordx4 v[166:167], v[162:165], off
	s_nop 1
	s_mov_b64 s[6:7], 0x240
	v_cvt_pk_bf16_f32 v91, v66, v67
	v_lshl_add_u64 v[160:161], v[182:183], 0, s[6:7]
	v_cvt_pk_bf16_f32 v90, v70, v71
	v_cvt_pk_bf16_f32 v92, v72, v73
	v_cvt_pk_bf16_f32 v93, v68, v69
	global_store_dwordx4 v[160:161], v[90:93], off
	s_nop 1
	v_cvt_pk_bf16_f32 v91, v152, v153
	v_lshl_add_u64 v[160:161], v[182:183], 0, 64
	v_cvt_pk_bf16_f32 v90, v150, v151
	v_cvt_pk_bf16_f32 v92, v156, v157
	v_cvt_pk_bf16_f32 v93, v158, v159
	global_store_dwordx4 v[160:161], v[90:93], off
	s_nop 1
	v_and_b32_e32 v91, 64, v205
	v_xor_b32_e32 v90, 16, v205
	v_add_u32_e32 v91, 64, v91
	v_cmp_lt_i32_e32 vcc, v90, v91
	s_mov_b32 s6, 0xf800000
	v_pk_add_f32 v[166:167], v[148:149], -1.0 op_sel_hi:[1,0]
	v_cndmask_b32_e32 v90, v205, v90, vcc
	v_lshlrev_b32_e32 v131, 2, v90
	s_waitcnt lgkmcnt(0)
	v_mov_b32_e32 v90, v129
	s_nop 1
	v_permlane16_swap_b32_e32 v129, v90
	v_add_f32_e32 v90, v129, v90
	v_mov_b32_e32 v91, v90
	s_nop 1
	v_permlane32_swap_b32_e32 v90, v91
	v_add_f32_e32 v90, v90, v91
	v_cmp_gt_f32_e32 vcc, s6, v90
	v_mul_f32_e32 v91, 0x4f800000, v90
	s_nop 0
	v_cndmask_b32_e32 v90, v90, v91, vcc
	v_sqrt_f32_e32 v91, v90
	s_nop 0
	v_add_u32_e32 v92, -1, v91
	v_fma_f32 v93, -v92, v91, v90
	v_cmp_ge_f32_e64 s[46:47], 0, v93
	v_add_u32_e32 v93, 1, v91
	s_nop 0
	v_cndmask_b32_e64 v92, v91, v92, s[46:47]
	v_fma_f32 v91, -v93, v91, v90
	v_cmp_lt_f32_e64 s[46:47], 0, v91
	s_nop 1
	v_cndmask_b32_e64 v91, v92, v93, s[46:47]
	v_mul_f32_e32 v92, 0x37800000, v91
	v_cndmask_b32_e32 v91, v91, v92, vcc
	v_cmp_class_f32_e32 vcc, v90, v207
	s_nop 1
	v_cndmask_b32_e32 v90, v91, v90, vcc
	v_max_f32_e32 v90, 0x2b8cbccc, v90
	v_div_scale_f32 v91, s[6:7], v90, v90, 1.0
	v_rcp_f32_e32 v92, v91
	s_mov_b64 s[6:7], 0x180
	v_fma_f32 v93, -v91, v92, 1.0
	v_fmac_f32_e32 v92, v93, v92
	v_div_scale_f32 v93, vcc, 1.0, v90, 1.0
	v_mul_f32_e32 v129, v93, v92
	v_fma_f32 v150, -v91, v129, v93
	v_fmac_f32_e32 v129, v150, v92
	v_fma_f32 v91, -v91, v129, v93
	v_div_fmas_f32 v91, v91, v92, v129
	v_div_fixup_f32 v160, v91, v90, 1.0
	ds_read_b128 v[90:93], v223 offset:40960
	ds_read_b128 v[150:153], v223 offset:40976
	ds_read_b128 v[156:159], v223 offset:43008
	v_pk_mul_f32 v[162:163], v[178:179], v[160:161] op_sel_hi:[1,0]
	v_pk_add_f32 v[178:179], v[146:147], -1.0 op_sel_hi:[1,0]
	s_waitcnt lgkmcnt(2)
	v_pk_fma_f32 v[92:93], v[166:167], v[92:93], 1.0 op_sel_hi:[1,1,0]
	v_pk_fma_f32 v[90:91], v[178:179], v[90:91], 1.0 op_sel_hi:[1,1,0]
	v_pk_mul_f32 v[166:167], v[172:173], v[92:93]
	v_pk_mul_f32 v[172:173], v[174:175], v[90:91]
	v_pk_mul_f32 v[92:93], v[168:169], v[166:167]
	v_pk_mul_f32 v[90:91], v[170:171], v[172:173]
	s_waitcnt lgkmcnt(0)
	v_pk_mul_f32 v[92:93], v[158:159], v[92:93]
	v_pk_mul_f32 v[90:91], v[156:157], v[90:91]
	v_pk_mul_f32 v[164:165], v[180:181], v[160:161] op_sel_hi:[1,0]
	v_add_f32_e32 v90, v90, v91
	v_add_f32_e32 v91, v92, v93
	v_add_f32_e32 v90, v90, v91
	v_add_f32_e32 v129, 0, v90
	ds_read_b128 v[90:93], v223 offset:43024
	v_xor_b32_e32 v161, 0x80000000, v165
	v_xor_b32_e32 v168, 0x80000000, v164
	v_xor_b32_e32 v169, 0x80000000, v163
	v_xor_b32_e32 v170, 0x80000000, v162
	v_pk_mul_f32 v[148:149], v[148:149], v[164:165]
	v_pk_mul_f32 v[146:147], v[146:147], v[162:163]
	v_pk_add_f32 v[162:163], v[144:145], -1.0 op_sel_hi:[1,0]
	v_pk_add_f32 v[164:165], v[142:143], -1.0 op_sel_hi:[1,0]
	v_pk_fma_f32 v[152:153], v[162:163], v[152:153], 1.0 op_sel_hi:[1,1,0]
	v_pk_fma_f32 v[150:151], v[164:165], v[150:151], 1.0 op_sel_hi:[1,1,0]
	v_pk_mul_f32 v[152:153], v[188:189], v[152:153]
	v_pk_mul_f32 v[150:151], v[190:191], v[150:151]
	v_pk_mul_f32 v[164:165], v[184:185], v[152:153]
	v_pk_mul_f32 v[162:163], v[186:187], v[150:151]
	s_waitcnt lgkmcnt(0)
	v_pk_mul_f32 v[92:93], v[92:93], v[164:165]
	v_pk_mul_f32 v[90:91], v[90:91], v[162:163]
	v_pk_mul_f32 v[156:157], v[194:195], v[160:161] op_sel_hi:[1,0]
	v_add_f32_e32 v90, v90, v91
	v_add_f32_e32 v91, v92, v93
	v_pk_mul_f32 v[158:159], v[196:197], v[160:161] op_sel_hi:[1,0]
	v_add_f32_e32 v90, v90, v91
	v_add_f32_e32 v129, v129, v90
	v_xor_b32_e32 v162, 0x80000000, v159
	v_xor_b32_e32 v163, 0x80000000, v158
	v_xor_b32_e32 v164, 0x80000000, v157
	v_xor_b32_e32 v165, 0x80000000, v156
	v_pk_mul_f32 v[142:143], v[142:143], v[156:157]
	v_lshl_add_u64 v[156:157], v[182:183], 0, s[30:31]
	v_cvt_pk_bf16_f32 v90, v172, v173
	v_cvt_pk_bf16_f32 v91, v166, v167
	v_cvt_pk_bf16_f32 v92, v150, v151
	v_cvt_pk_bf16_f32 v93, v152, v153
	global_store_dwordx4 v[156:157], v[90:93], off
	s_nop 1
	v_pk_mul_f32 v[144:145], v[144:145], v[158:159]
	v_lshl_add_u64 v[150:151], v[182:183], 0, s[34:35]
	v_cvt_pk_bf16_f32 v90, v170, v169
	v_cvt_pk_bf16_f32 v91, v168, v161
	v_cvt_pk_bf16_f32 v92, v165, v164
	v_cvt_pk_bf16_f32 v93, v163, v162
	global_store_dwordx4 v[150:151], v[90:93], off
	s_nop 1
	v_lshl_add_u64 v[150:151], v[182:183], 0, s[6:7]
	v_cvt_pk_bf16_f32 v90, v146, v147
	v_cvt_pk_bf16_f32 v91, v148, v149
	v_cvt_pk_bf16_f32 v92, v142, v143
	v_cvt_pk_bf16_f32 v93, v144, v145
	global_store_dwordx4 v[150:151], v[90:93], off
	s_nop 1
	ds_read_b128 v[90:93], v223 offset:41088
	ds_read_b128 v[142:145], v223 offset:41104
	ds_read_b128 v[146:149], v223 offset:43136
	v_pk_add_f32 v[150:151], v[140:141], -1.0 op_sel_hi:[1,0]
	v_pk_add_f32 v[152:153], v[138:139], -1.0 op_sel_hi:[1,0]
	s_waitcnt lgkmcnt(2)
	v_pk_fma_f32 v[92:93], v[150:151], v[92:93], 1.0 op_sel_hi:[1,1,0]
	v_pk_fma_f32 v[90:91], v[152:153], v[90:91], 1.0 op_sel_hi:[1,1,0]
	v_pk_mul_f32 v[78:79], v[78:79], v[92:93]
	v_pk_mul_f32 v[74:75], v[74:75], v[90:91]
	v_pk_mul_f32 v[66:67], v[66:67], v[78:79]
	v_pk_mul_f32 v[70:71], v[70:71], v[74:75]
	s_waitcnt lgkmcnt(0)
	v_pk_mul_f32 v[66:67], v[148:149], v[66:67]
	v_pk_mul_f32 v[70:71], v[146:147], v[70:71]
	v_add_f32_e32 v66, v66, v67
	v_add_f32_e32 v70, v70, v71
	v_pk_mul_f32 v[82:83], v[82:83], v[160:161] op_sel_hi:[1,0]
	v_add_f32_e32 v66, v70, v66
	v_add_f32_e32 v129, v129, v66
	v_xor_b32_e32 v146, 0x80000000, v83
	v_xor_b32_e32 v147, 0x80000000, v82
	v_pk_mul_f32 v[70:71], v[140:141], v[82:83]
	v_pk_mul_f32 v[66:67], v[88:89], v[160:161] op_sel_hi:[1,0]
	v_pk_mul_f32 v[88:89], v[84:85], v[160:161] op_sel_hi:[1,0]
	ds_read_b128 v[82:85], v223 offset:43152
	v_pk_add_f32 v[90:91], v[136:137], -1.0 op_sel_hi:[1,0]
	v_pk_add_f32 v[92:93], v[134:135], -1.0 op_sel_hi:[1,0]
	v_pk_fma_f32 v[90:91], v[90:91], v[144:145], 1.0 op_sel_hi:[1,1,0]
	v_pk_fma_f32 v[92:93], v[92:93], v[142:143], 1.0 op_sel_hi:[1,1,0]
	v_pk_mul_f32 v[80:81], v[80:81], v[90:91]
	v_pk_mul_f32 v[76:77], v[76:77], v[92:93]
	v_pk_mul_f32 v[68:69], v[68:69], v[80:81]
	v_pk_mul_f32 v[72:73], v[72:73], v[76:77]
	s_waitcnt lgkmcnt(0)
	v_pk_mul_f32 v[68:69], v[84:85], v[68:69]
	v_pk_mul_f32 v[72:73], v[82:83], v[72:73]
	v_add_f32_e32 v68, v68, v69
	v_add_f32_e32 v72, v72, v73
	v_pk_mul_f32 v[86:87], v[86:87], v[160:161] op_sel_hi:[1,0]
	v_add_f32_e32 v68, v72, v68
	v_xor_b32_e32 v148, 0x80000000, v87
	v_xor_b32_e32 v149, 0x80000000, v86
	v_add_f32_e32 v90, v129, v68
	v_xor_b32_e32 v129, 0x80000000, v66
	v_pk_mul_f32 v[82:83], v[134:135], v[66:67]
	s_mov_b64 s[6:7], 0xc0
	v_cvt_pk_bf16_f32 v66, v74, v75
	v_pk_mul_f32 v[86:87], v[138:139], v[86:87]
	v_xor_b32_e32 v91, 0x80000000, v89
	v_xor_b32_e32 v92, 0x80000000, v88
	v_xor_b32_e32 v93, 0x80000000, v67
	v_lshl_add_u64 v[84:85], v[182:183], 0, s[6:7]
	v_cvt_pk_bf16_f32 v67, v78, v79
	v_cvt_pk_bf16_f32 v68, v76, v77
	v_cvt_pk_bf16_f32 v69, v80, v81
	global_store_dwordx4 v[84:85], v[66:69], off
	s_nop 1
	s_mov_b64 s[6:7], 0x140
	v_cvt_pk_bf16_f32 v66, v149, v148
	v_pk_mul_f32 v[72:73], v[136:137], v[88:89]
	v_lshl_add_u64 v[74:75], v[182:183], 0, s[6:7]
	v_cvt_pk_bf16_f32 v67, v147, v146
	v_cvt_pk_bf16_f32 v68, v129, v93
	v_cvt_pk_bf16_f32 v69, v92, v91
	global_store_dwordx4 v[74:75], v[66:69], off
	s_nop 1
	s_mov_b64 s[6:7], 0x1c0
	v_cvt_pk_bf16_f32 v66, v86, v87
	v_lshl_add_u64 v[74:75], v[182:183], 0, s[6:7]
	v_cvt_pk_bf16_f32 v67, v70, v71
	v_cvt_pk_bf16_f32 v68, v82, v83
	v_cvt_pk_bf16_f32 v69, v72, v73
	global_store_dwordx4 v[74:75], v[66:69], off
	s_nop 1
	ds_bpermute_b32 v66, v131, v90
	s_waitcnt lgkmcnt(0)
	v_add_f32_e32 v66, v90, v66
	v_mov_b32_e32 v67, v66
	s_nop 1
	v_permlane32_swap_b32_e32 v66, v67
	s_and_saveexec_b64 s[46:47], s[44:45]
	s_cbranch_execz .LBB0_912
	v_add_f32_e32 v68, v66, v67
	v_lshlrev_b64 v[66:67], 5, v[132:133]
	v_lshl_add_u64 v[66:67], s[58:59], 0, v[66:67]
	global_store_dword v[66:67], v68, off
.LBB0_912:
	s_or_b64 exec, exec, s[46:47]
	ds_read_b128 v[70:73], v224 offset:8448
	v_add_u32_e32 v66, 16, v132
	v_ashrrev_i32_e32 v67, 31, v66
	s_mov_b64 s[6:7], 0x7800400
	v_or_b32_e32 v68, 16, v128
	s_waitcnt lgkmcnt(0)
	v_mfma_f32_16x16x32_bf16 v[44:47], v[44:47], v[70:73], 0
	v_ashrrev_i32_e32 v69, 31, v68
	v_cmp_lt_i32_e32 vcc, -1, v227
	v_mfma_f32_16x16x32_bf16 v[50:53], v[50:53], v[70:73], 0
	s_nop 0
	v_cndmask_b32_e32 v128, 0, v210, vcc
	v_mfma_f32_16x16x32_bf16 v[54:57], v[54:57], v[70:73], 0
	v_mfma_f32_16x16x32_bf16 v[58:61], v[58:61], v[70:73], 0
	ds_read_b128 v[70:73], v224 offset:8512
	s_waitcnt lgkmcnt(0)
	v_mfma_f32_16x16x32_bf16 v[32:35], v[32:35], v[70:73], v[44:47]
	v_mfma_f32_16x16x32_bf16 v[36:39], v[36:39], v[70:73], v[50:53]
	v_mfma_f32_16x16x32_bf16 v[50:53], v[62:65], v[70:73], v[58:61]
	s_nop 0
	ds_read_b128 v[44:47], v222 offset:45056
	s_nop 0
	ds_read_b128 v[58:61], v222 offset:45072
	s_waitcnt lgkmcnt(1)
	s_nop 0
	v_add_f32_e32 v32, v32, v44
	v_add_f32_e32 v33, v33, v45
	v_mul_f32_e32 v32, 0xbfb8aa3b, v32
	v_mul_f32_e32 v33, 0xbfb8aa3b, v33
	v_exp_f32_e32 v32, v32
	v_exp_f32_e32 v33, v33
	v_mfma_f32_16x16x32_bf16 v[40:43], v[40:43], v[70:73], v[54:57]
	v_cndmask_b32_e64 v72, 0, 1.0, vcc
	v_add_f32_e32 v32, 1.0, v32
	v_add_f32_e32 v33, 1.0, v33
	v_rcp_f32_e32 v32, v32
	v_rcp_f32_e32 v33, v33
	s_nop 0
	v_pk_mul_f32 v[54:55], v[32:33], s[72:73] op_sel_hi:[1,0]
	v_add_f32_e32 v32, v34, v46
	v_add_f32_e32 v33, v35, v47
	v_mul_f32_e32 v32, 0xbfb8aa3b, v32
	v_mul_f32_e32 v33, 0xbfb8aa3b, v33
	v_exp_f32_e32 v32, v32
	v_exp_f32_e32 v33, v33
	v_add_f32_e32 v32, 1.0, v32
	v_add_f32_e32 v33, 1.0, v33
	v_rcp_f32_e32 v32, v32
	v_rcp_f32_e32 v33, v33
	s_nop 0
	v_pk_mul_f32 v[56:57], v[32:33], s[72:73] op_sel_hi:[1,0]
	s_waitcnt lgkmcnt(0)
	v_add_f32_e32 v32, v36, v58
	v_add_f32_e32 v33, v37, v59
	v_mul_f32_e32 v32, 0xbfb8aa3b, v32
	v_mul_f32_e32 v33, 0xbfb8aa3b, v33
	v_exp_f32_e32 v32, v32
	v_exp_f32_e32 v33, v33
	v_add_f32_e32 v32, 1.0, v32
	v_add_f32_e32 v33, 1.0, v33
	v_rcp_f32_e32 v32, v32
	v_rcp_f32_e32 v33, v33
	s_nop 0
	v_pk_mul_f32 v[58:59], v[32:33], s[72:73] op_sel_hi:[1,0]
	v_add_f32_e32 v32, v38, v60
	v_add_f32_e32 v33, v39, v61
	v_mul_f32_e32 v32, 0xbfb8aa3b, v32
	v_mul_f32_e32 v33, 0xbfb8aa3b, v33
	v_exp_f32_e32 v32, v32
	v_exp_f32_e32 v33, v33
	v_add_f32_e32 v32, 1.0, v32
	v_add_f32_e32 v33, 1.0, v33
	v_rcp_f32_e32 v32, v32
	v_rcp_f32_e32 v33, v33
	s_nop 0
	v_pk_mul_f32 v[60:61], v[32:33], s[72:73] op_sel_hi:[1,0]
	ds_read_b128 v[32:35], v222 offset:45184
	s_waitcnt lgkmcnt(0)
	v_add_f32_e32 v32, v40, v32
	v_add_f32_e32 v33, v41, v33
	v_mul_f32_e32 v32, 0xbfb8aa3b, v32
	v_mul_f32_e32 v33, 0xbfb8aa3b, v33
	v_exp_f32_e32 v32, v32
	v_exp_f32_e32 v33, v33
	v_add_f32_e32 v32, 1.0, v32
	v_add_f32_e32 v33, 1.0, v33
	v_rcp_f32_e32 v32, v32
	v_rcp_f32_e32 v33, v33
	s_nop 0
	v_pk_mul_f32 v[44:45], v[32:33], s[72:73] op_sel_hi:[1,0]
	v_add_f32_e32 v32, v42, v34
	v_add_f32_e32 v33, v43, v35
	v_mul_f32_e32 v32, 0xbfb8aa3b, v32
	v_mul_f32_e32 v33, 0xbfb8aa3b, v33
	v_exp_f32_e32 v32, v32
	v_exp_f32_e32 v33, v33
	v_add_f32_e32 v32, 1.0, v32
	v_add_f32_e32 v33, 1.0, v33
	v_rcp_f32_e32 v32, v32
	v_rcp_f32_e32 v33, v33
	s_nop 0
	v_pk_mul_f32 v[46:47], v[32:33], s[72:73] op_sel_hi:[1,0]
	ds_read_b128 v[32:35], v222 offset:45200
	s_waitcnt lgkmcnt(0)
	v_add_f32_e32 v32, v50, v32
	v_add_f32_e32 v33, v51, v33
	v_mul_f32_e32 v32, 0xbfb8aa3b, v32
	v_mul_f32_e32 v33, 0xbfb8aa3b, v33
	v_exp_f32_e32 v32, v32
	v_exp_f32_e32 v33, v33
	v_add_f32_e32 v32, 1.0, v32
	v_add_f32_e32 v33, 1.0, v33
	v_rcp_f32_e32 v32, v32
	v_rcp_f32_e32 v33, v33
	s_nop 0
	v_pk_mul_f32 v[50:51], v[32:33], s[72:73] op_sel_hi:[1,0]
	v_add_f32_e32 v32, v52, v34
	v_add_f32_e32 v33, v53, v35
	v_mul_f32_e32 v32, 0xbfb8aa3b, v32
	v_mul_f32_e32 v33, 0xbfb8aa3b, v33
	v_exp_f32_e32 v32, v32
	v_exp_f32_e32 v33, v33
	v_add_f32_e32 v32, 1.0, v32
	v_add_f32_e32 v33, 1.0, v33
	v_rcp_f32_e32 v32, v32
	v_rcp_f32_e32 v33, v33
	s_nop 0
	v_pk_mul_f32 v[52:53], v[32:33], s[72:73] op_sel_hi:[1,0]
	ds_read_b128 v[32:35], v224 offset:8576
	s_waitcnt lgkmcnt(0)
	v_mfma_f32_16x16x32_bf16 v[0:3], v[0:3], v[32:35], 0
	v_mfma_f32_16x16x32_bf16 v[4:7], v[4:7], v[32:35], 0
	v_mfma_f32_16x16x32_bf16 v[8:11], v[8:11], v[32:35], 0
	v_mfma_f32_16x16x32_bf16 v[12:15], v[12:15], v[32:35], 0
	ds_read_b128 v[32:35], v224 offset:8640
	s_waitcnt lgkmcnt(0)
	v_mfma_f32_16x16x32_bf16 v[0:3], v[16:19], v[32:35], v[0:3]
	ds_read_b128 v[16:19], v222 offset:47104
	v_mfma_f32_16x16x32_bf16 v[4:7], v[20:23], v[32:35], v[4:7]
	global_load_dwordx4 v[20:23], v[112:113], off offset:64
	s_waitcnt lgkmcnt(0)
	s_nop 3
	v_add_f32_e32 v0, v0, v16
	v_mul_f32_e32 v0, 0xbfb8aa3b, v0
	v_exp_f32_e32 v0, v0
	v_mfma_f32_16x16x32_bf16 v[8:11], v[24:27], v[32:35], v[8:11]
	v_add_f32_e32 v0, 1.0, v0
	v_rcp_f32_e32 v40, v0
	v_add_f32_e32 v0, v1, v17
	v_mul_f32_e32 v0, 0xbfb8aa3b, v0
	v_exp_f32_e32 v0, v0
	v_mfma_f32_16x16x32_bf16 v[12:15], v[28:31], v[32:35], v[12:15]
	v_add_f32_e32 v0, 1.0, v0
	v_rcp_f32_e32 v41, v0
	v_add_f32_e32 v0, v2, v18
	v_mul_f32_e32 v0, 0xbfb8aa3b, v0
	v_exp_f32_e32 v0, v0
	s_nop 0
	v_add_f32_e32 v0, 1.0, v0
	v_rcp_f32_e32 v42, v0
	v_add_f32_e32 v0, v3, v19
	v_mul_f32_e32 v0, 0xbfb8aa3b, v0
	v_exp_f32_e32 v0, v0
	global_load_dwordx4 v[16:19], v[118:119], off
	v_add_f32_e32 v0, 1.0, v0
	v_rcp_f32_e32 v43, v0
	ds_read_b128 v[0:3], v222 offset:47120
	s_waitcnt lgkmcnt(0)
	v_add_f32_e32 v0, v4, v0
	v_mul_f32_e32 v0, 0xbfb8aa3b, v0
	v_exp_f32_e32 v0, v0
	s_nop 0
	v_add_f32_e32 v0, 1.0, v0
	v_rcp_f32_e32 v36, v0
	v_add_f32_e32 v0, v5, v1
	v_mul_f32_e32 v0, 0xbfb8aa3b, v0
	v_exp_f32_e32 v0, v0
	s_nop 0
	v_add_f32_e32 v0, 1.0, v0
	v_rcp_f32_e32 v37, v0
	v_add_f32_e32 v0, v6, v2
	v_mul_f32_e32 v0, 0xbfb8aa3b, v0
	v_exp_f32_e32 v0, v0
	s_nop 0
	v_add_f32_e32 v0, 1.0, v0
	v_rcp_f32_e32 v38, v0
	v_add_f32_e32 v0, v7, v3
	v_mul_f32_e32 v0, 0xbfb8aa3b, v0
	v_exp_f32_e32 v0, v0
	global_load_dwordx4 v[4:7], v[112:113], off
	v_add_f32_e32 v0, 1.0, v0
	v_rcp_f32_e32 v39, v0
	ds_read_b128 v[0:3], v222 offset:47232
	s_waitcnt lgkmcnt(0)
	v_add_f32_e32 v0, v8, v0
	v_mul_f32_e32 v0, 0xbfb8aa3b, v0
	v_exp_f32_e32 v0, v0
	s_nop 0
	v_add_f32_e32 v0, 1.0, v0
	v_rcp_f32_e32 v32, v0
	v_add_f32_e32 v0, v9, v1
	v_mul_f32_e32 v0, 0xbfb8aa3b, v0
	v_exp_f32_e32 v0, v0
	s_nop 0
	v_add_f32_e32 v0, 1.0, v0
	v_rcp_f32_e32 v33, v0
	v_add_f32_e32 v0, v10, v2
	v_mul_f32_e32 v0, 0xbfb8aa3b, v0
	v_exp_f32_e32 v0, v0
	s_nop 0
	v_add_f32_e32 v0, 1.0, v0
	v_rcp_f32_e32 v34, v0
	v_add_f32_e32 v0, v11, v3
	v_mul_f32_e32 v0, 0xbfb8aa3b, v0
	v_exp_f32_e32 v0, v0
	global_load_dwordx4 v[8:11], v[114:115], off
	global_load_dwordx4 v[242:245], v[114:115], off offset:64
	global_load_dwordx4 v[246:249], v[116:117], off offset:64
	global_load_dwordx4 v[250:253], v[118:119], off offset:64
	v_add_f32_e32 v0, 1.0, v0
	v_rcp_f32_e32 v35, v0
	ds_read_b128 v[0:3], v222 offset:47248
	s_waitcnt lgkmcnt(0)
	v_add_f32_e32 v0, v12, v0
	v_mul_f32_e32 v0, 0xbfb8aa3b, v0
	v_exp_f32_e32 v0, v0
	s_nop 0
	v_add_f32_e32 v0, 1.0, v0
	v_rcp_f32_e32 v28, v0
	v_add_f32_e32 v0, v13, v1
	v_mul_f32_e32 v0, 0xbfb8aa3b, v0
	v_exp_f32_e32 v0, v0
	s_nop 0
	v_add_f32_e32 v0, 1.0, v0
	v_rcp_f32_e32 v29, v0
	v_add_f32_e32 v0, v14, v2
	v_mul_f32_e32 v0, 0xbfb8aa3b, v0
	v_exp_f32_e32 v0, v0
	s_nop 0
	v_add_f32_e32 v0, 1.0, v0
	v_rcp_f32_e32 v30, v0
	v_add_f32_e32 v0, v15, v3
	global_load_dwordx4 v[12:15], v[116:117], off
	v_mul_f32_e32 v0, 0xbfb8aa3b, v0
	v_exp_f32_e32 v0, v0
	s_nop 0
	v_add_f32_e32 v0, 1.0, v0
	v_rcp_f32_e32 v31, v0
	ds_read_b128 v[0:3], v224 offset:8704
	s_waitcnt vmcnt(5) lgkmcnt(0)
	v_mfma_f32_16x16x32_bf16 v[4:7], v[4:7], v[0:3], 0
	s_waitcnt vmcnt(4)
	v_mfma_f32_16x16x32_bf16 v[8:11], v[8:11], v[0:3], 0
	s_waitcnt vmcnt(0)
	v_mfma_f32_16x16x32_bf16 v[12:15], v[12:15], v[0:3], 0
	v_mfma_f32_16x16x32_bf16 v[0:3], v[16:19], v[0:3], 0
	ds_read_b128 v[16:19], v224 offset:8768
	s_waitcnt lgkmcnt(0)
	v_mfma_f32_16x16x32_bf16 v[4:7], v[20:23], v[16:19], v[4:7]
	global_load_dwordx4 v[20:23], v[112:113], off offset:128
	v_mfma_f32_16x16x32_bf16 v[8:11], v[242:245], v[16:19], v[8:11]
	global_load_dwordx4 v[242:245], v[114:115], off offset:128
	v_mfma_f32_16x16x32_bf16 v[12:15], v[246:249], v[16:19], v[12:15]
	global_load_dwordx4 v[246:249], v[116:117], off offset:128
	v_mfma_f32_16x16x32_bf16 v[0:3], v[250:253], v[16:19], v[0:3]
	global_load_dwordx4 v[250:253], v[118:119], off offset:128
	ds_read_b128 v[16:19], v224 offset:8832
	s_waitcnt vmcnt(3) lgkmcnt(0)
	v_mfma_f32_16x16x32_bf16 v[20:23], v[20:23], v[16:19], v[4:7]
	s_waitcnt vmcnt(2)
	v_mfma_f32_16x16x32_bf16 v[24:27], v[242:245], v[16:19], v[8:11]
	s_nop 2
	global_load_dwordx4 v[8:11], v[112:113], off offset:192
	global_load_dwordx4 v[242:245], v[116:117], off offset:192
	s_waitcnt vmcnt(3)
	v_mfma_f32_16x16x32_bf16 v[62:65], v[246:249], v[16:19], v[12:15]
	s_nop 2
	global_load_dwordx4 v[12:15], v[114:115], off offset:192
	global_load_dwordx4 v[246:249], v[118:119], off offset:192
	s_waitcnt vmcnt(4)
	v_mfma_f32_16x16x32_bf16 v[0:3], v[250:253], v[16:19], v[0:3]
	ds_read_b128 v[4:7], v224 offset:8896
	s_waitcnt vmcnt(3) lgkmcnt(0)
	v_mfma_f32_16x16x32_bf16 v[8:11], v[8:11], v[4:7], v[20:23]
	s_waitcnt vmcnt(1)
	v_mfma_f32_16x16x32_bf16 v[12:15], v[12:15], v[4:7], v[24:27]
	v_mfma_f32_16x16x32_bf16 v[16:19], v[242:245], v[4:7], v[62:65]
	s_waitcnt vmcnt(0)
	v_mfma_f32_16x16x32_bf16 v[0:3], v[246:249], v[4:7], v[0:3]
	v_lshlrev_b64 v[4:5], 11, v[66:67]
	v_lshl_add_u64 v[4:5], s[2:3], 0, v[4:5]
	v_lshl_add_u64 v[4:5], s[56:57], 1, v[4:5]
	v_lshl_add_u64 v[20:21], v[4:5], 0, v[48:49]
	v_lshl_add_u64 v[22:23], v[20:21], 0, s[6:7]
	v_cvt_pk_bf16_f32 v6, v12, v13
	s_mov_b64 s[6:7], 0x7800440
	v_cvt_pk_bf16_f32 v4, v8, v9
	v_cvt_pk_bf16_f32 v5, v10, v11
	v_cvt_pk_bf16_f32 v7, v14, v15
	global_store_dwordx4 v[22:23], v[4:7], off
	s_nop 1
	v_cvt_pk_bf16_f32 v6, v0, v1
	v_lshl_add_u64 v[0:1], v[20:21], 0, s[6:7]
	v_cvt_pk_bf16_f32 v4, v16, v17
	v_cvt_pk_bf16_f32 v5, v18, v19
	v_cvt_pk_bf16_f32 v7, v2, v3
	global_store_dwordx4 v[0:1], v[4:7], off
	s_nop 1
	v_lshl_add_u64 v[0:1], v[126:127], 0, v[68:69]
	v_mov_b64_e32 v[2:3], s[54:55]
	v_mad_u64_u32 v[78:79], s[6:7], v0, s95, v[2:3]
	v_mad_i32_i24 v79, v1, s95, v79
	v_mov_b64_e32 v[0:1], s[12:13]
	v_mad_i64_i32 v[132:133], s[6:7], v66, s19, v[0:1]
	v_ashrrev_i32_e32 v0, 31, v227
	v_not_b32_e32 v129, v0
	v_lshl_add_u64 v[12:13], v[120:121], 1, v[132:133]
	s_mov_b64 s[6:7], 0x800
	v_lshl_add_u64 v[8:9], v[12:13], 0, s[6:7]
	v_lshl_add_u64 v[16:17], v[12:13], 0, v[128:129]
	global_load_dwordx4 v[4:7], v[12:13], off offset:2048
	global_load_dwordx4 v[0:3], v[12:13], off offset:3072
	s_nop 0
	global_load_dwordx4 v[8:11], v[8:9], off offset:2048
	v_lshl_add_u64 v[20:21], v[16:17], 0, s[6:7]
	global_load_dwordx4 v[12:15], v[16:17], off offset:2048
	s_nop 0
	global_load_dwordx4 v[16:19], v[16:17], off offset:3072
	s_nop 0
	global_load_dwordx4 v[20:23], v[20:21], off offset:2048
	ds_read_b128 v[68:71], v223 offset:32768
	ds_read_b128 v[24:27], v223 offset:32784
	ds_read_b128 v[74:77], v223 offset:34816
	ds_read_b128 v[80:83], v223 offset:36864
	v_lshl_add_u64 v[78:79], v[78:79], 0, v[48:49]
	s_mov_b64 s[6:7], 0x280
	s_waitcnt vmcnt(5)
	v_lshlrev_b32_e32 v64, 16, v4
	v_and_b32_e32 v65, 0xffff0000, v4
	v_lshlrev_b32_e32 v4, 16, v5
	v_and_b32_e32 v5, 0xffff0000, v5
	s_waitcnt vmcnt(2)
	v_lshlrev_b32_e32 v62, 16, v12
	v_and_b32_e32 v63, 0xffff0000, v12
	v_xor_b32_e32 v93, 0x80000000, v65
	v_xor_b32_e32 v92, 0x80000000, v64
	v_lshlrev_b32_e32 v12, 16, v13
	v_and_b32_e32 v13, 0xffff0000, v13
	v_pk_fma_f32 v[92:93], v[72:73], v[62:63], v[92:93] op_sel_hi:[0,1,1]
	v_xor_b32_e32 v63, 0x80000000, v5
	v_xor_b32_e32 v62, 0x80000000, v4
	v_lshlrev_b32_e32 v84, 16, v0
	v_and_b32_e32 v85, 0xffff0000, v0
	v_lshlrev_b32_e32 v0, 16, v1
	v_and_b32_e32 v1, 0xffff0000, v1
	v_pk_fma_f32 v[12:13], v[72:73], v[12:13], v[62:63] op_sel_hi:[0,1,1]
	s_waitcnt vmcnt(1)
	v_lshlrev_b32_e32 v88, 16, v16
	v_and_b32_e32 v89, 0xffff0000, v16
	v_lshlrev_b32_e32 v16, 16, v17
	v_and_b32_e32 v17, 0xffff0000, v17
	s_waitcnt lgkmcnt(3)
	v_pk_fma_f32 v[62:63], v[70:71], v[12:13], v[4:5]
	v_xor_b32_e32 v5, 0x80000000, v85
	v_xor_b32_e32 v4, 0x80000000, v84
	v_xor_b32_e32 v13, 0x80000000, v1
	v_xor_b32_e32 v12, 0x80000000, v0
	v_pk_fma_f32 v[4:5], v[72:73], v[88:89], v[4:5] op_sel_hi:[0,1,1]
	v_pk_fma_f32 v[12:13], v[72:73], v[16:17], v[12:13] op_sel_hi:[0,1,1]
	v_pk_fma_f32 v[64:65], v[68:69], v[92:93], v[64:65]
	s_waitcnt lgkmcnt(1)
	v_pk_fma_f32 v[68:69], v[76:77], v[12:13], v[0:1]
	v_pk_fma_f32 v[70:71], v[74:75], v[4:5], v[84:85]
	ds_read_b128 v[74:77], v223 offset:38912
	v_lshlrev_b32_e32 v86, 16, v8
	v_and_b32_e32 v87, 0xffff0000, v8
	v_lshlrev_b32_e32 v8, 16, v9
	v_and_b32_e32 v9, 0xffff0000, v9
	s_waitcnt vmcnt(0)
	v_lshlrev_b32_e32 v90, 16, v20
	v_and_b32_e32 v91, 0xffff0000, v20
	v_xor_b32_e32 v1, 0x80000000, v87
	v_xor_b32_e32 v0, 0x80000000, v86
	v_lshlrev_b32_e32 v20, 16, v21
	v_and_b32_e32 v21, 0xffff0000, v21
	v_pk_fma_f32 v[4:5], v[72:73], v[90:91], v[0:1] op_sel_hi:[0,1,1]
	v_xor_b32_e32 v1, 0x80000000, v9
	v_xor_b32_e32 v0, 0x80000000, v8
	v_pk_fma_f32 v[0:1], v[72:73], v[20:21], v[0:1] op_sel_hi:[0,1,1]
	s_waitcnt lgkmcnt(0)
	v_pk_mul_f32 v[74:75], v[74:75], v[70:71]
	v_pk_mul_f32 v[76:77], v[76:77], v[68:69]
	v_pk_fma_f32 v[0:1], v[82:83], v[0:1], v[8:9]
	v_pk_mul_f32 v[8:9], v[76:77], v[76:77]
	v_pk_mul_f32 v[12:13], v[74:75], v[74:75]
	v_lshlrev_b32_e32 v20, 16, v6
	v_pk_mov_b32 v[16:17], v[12:13], v[8:9] op_sel:[1,0]
	v_mov_b32_e32 v13, v9
	v_pk_add_f32 v[8:9], v[16:17], v[12:13]
	v_and_b32_e32 v21, 0xffff0000, v6
	v_pk_fma_f32 v[4:5], v[80:81], v[4:5], v[86:87]
	v_pk_add_f32 v[88:89], v[8:9], v[8:9] op_sel_hi:[0,1]
	v_lshlrev_b32_e32 v80, 16, v7
	v_and_b32_e32 v81, 0xffff0000, v7
	v_lshlrev_b32_e32 v86, 16, v2
	v_and_b32_e32 v87, 0xffff0000, v2
	v_lshlrev_b32_e32 v84, 16, v3
	v_and_b32_e32 v85, 0xffff0000, v3
	v_lshlrev_b32_e32 v2, 16, v10
	v_and_b32_e32 v3, 0xffff0000, v10
	v_lshlrev_b32_e32 v6, 16, v11
	v_and_b32_e32 v7, 0xffff0000, v11
	v_lshlrev_b32_e32 v82, 16, v14
	v_and_b32_e32 v83, 0xffff0000, v14
	v_lshlrev_b32_e32 v10, 16, v22
	v_and_b32_e32 v11, 0xffff0000, v22
	v_lshlrev_b32_e32 v8, 16, v23
	v_and_b32_e32 v9, 0xffff0000, v23
	v_xor_b32_e32 v23, 0x80000000, v21
	v_xor_b32_e32 v22, 0x80000000, v20
	v_lshlrev_b32_e32 v90, 16, v15
	v_and_b32_e32 v91, 0xffff0000, v15
	v_lshlrev_b32_e32 v92, 16, v18
	v_and_b32_e32 v93, 0xffff0000, v18
	v_lshlrev_b32_e32 v126, 16, v19
	v_and_b32_e32 v127, 0xffff0000, v19
	ds_read_b128 v[12:15], v223 offset:34832
	ds_read_b128 v[16:19], v223 offset:36880
	v_pk_fma_f32 v[22:23], v[72:73], v[82:83], v[22:23] op_sel_hi:[0,1,1]
	v_xor_b32_e32 v83, 0x80000000, v81
	v_xor_b32_e32 v82, 0x80000000, v80
	v_pk_fma_f32 v[82:83], v[72:73], v[90:91], v[82:83] op_sel_hi:[0,1,1]
	v_pk_fma_f32 v[80:81], v[26:27], v[82:83], v[80:81]
	v_pk_fma_f32 v[82:83], v[24:25], v[22:23], v[20:21]
	v_xor_b32_e32 v21, 0x80000000, v87
	v_xor_b32_e32 v20, 0x80000000, v86
	v_pk_fma_f32 v[20:21], v[72:73], v[92:93], v[20:21] op_sel_hi:[0,1,1]
	s_waitcnt lgkmcnt(1)
	v_pk_fma_f32 v[86:87], v[12:13], v[20:21], v[86:87]
	v_xor_b32_e32 v13, 0x80000000, v3
	v_xor_b32_e32 v12, 0x80000000, v2
	v_pk_fma_f32 v[10:11], v[72:73], v[10:11], v[12:13] op_sel_hi:[0,1,1]
	v_xor_b32_e32 v13, 0x80000000, v7
	v_xor_b32_e32 v12, 0x80000000, v6
	v_pk_fma_f32 v[8:9], v[72:73], v[8:9], v[12:13] op_sel_hi:[0,1,1]
	s_waitcnt lgkmcnt(0)
	v_pk_fma_f32 v[12:13], v[18:19], v[8:9], v[6:7]
	ds_read_b128 v[6:9], v223 offset:38928
	v_xor_b32_e32 v23, 0x80000000, v85
	v_xor_b32_e32 v22, 0x80000000, v84
	v_pk_fma_f32 v[22:23], v[72:73], v[126:127], v[22:23] op_sel_hi:[0,1,1]
	v_pk_fma_f32 v[84:85], v[14:15], v[22:23], v[84:85]
	s_waitcnt lgkmcnt(0)
	v_pk_mul_f32 v[90:91], v[6:7], v[86:87]
	v_pk_mul_f32 v[92:93], v[8:9], v[84:85]
	v_pk_fma_f32 v[10:11], v[16:17], v[10:11], v[2:3]
	v_pk_mul_f32 v[2:3], v[92:93], v[92:93]
	v_pk_mul_f32 v[6:7], v[90:91], v[90:91]
	s_nop 0
	v_pk_mov_b32 v[8:9], v[6:7], v[2:3] op_sel:[1,0]
	v_mov_b32_e32 v7, v3
	v_pk_add_f32 v[2:3], v[8:9], v[6:7]
	v_lshl_add_u64 v[6:7], v[78:79], 0, s[6:7]
	v_pk_add_f32 v[126:127], v[2:3], v[2:3] op_sel_hi:[0,1]
	v_cvt_pk_bf16_f32 v2, v4, v5
	v_cvt_pk_bf16_f32 v3, v0, v1
	v_cvt_pk_bf16_f32 v4, v10, v11
	v_cvt_pk_bf16_f32 v5, v12, v13
	global_store_dwordx4 v[6:7], v[2:5], off
	s_nop 1
	s_mov_b64 s[6:7], 0x200
	v_lshl_add_u64 v[4:5], v[78:79], 0, s[6:7]
	v_cvt_pk_bf16_f32 v0, v64, v65
	v_cvt_pk_bf16_f32 v1, v62, v63
	v_cvt_pk_bf16_f32 v2, v82, v83
	v_cvt_pk_bf16_f32 v3, v80, v81
	global_store_dwordx4 v[4:5], v[0:3], off
	s_nop 1
	v_lshl_add_u64 v[12:13], v[122:123], 1, v[132:133]
	s_mov_b64 s[6:7], 0x840
	v_cvt_pk_bf16_f32 v0, v54, v55
	v_cvt_pk_bf16_f32 v1, v56, v57
	v_cvt_pk_bf16_f32 v2, v58, v59
	v_cvt_pk_bf16_f32 v3, v60, v61
	global_store_dwordx4 v[78:79], v[0:3], off
	s_nop 1
	v_lshl_add_u64 v[8:9], v[12:13], 0, s[6:7]
	v_lshl_add_u64 v[16:17], v[12:13], 0, v[128:129]
	global_load_dwordx4 v[0:3], v[12:13], off offset:2112
	global_load_dwordx4 v[4:7], v[12:13], off offset:3136
	s_nop 0
	global_load_dwordx4 v[8:11], v[8:9], off offset:2048
	v_lshl_add_u64 v[20:21], v[16:17], 0, s[6:7]
	global_load_dwordx4 v[12:15], v[16:17], off offset:2112
	s_nop 0
	global_load_dwordx4 v[16:19], v[16:17], off offset:3136
	s_nop 0
	global_load_dwordx4 v[20:23], v[20:21], off offset:2048
	ds_read_b128 v[54:57], v223 offset:32896
	ds_read_b128 v[24:27], v223 offset:32912
	ds_read_b128 v[58:61], v223 offset:34944
	ds_read_b128 v[132:135], v223 offset:36992
	s_mov_b64 s[6:7], 0x2c0
	s_waitcnt vmcnt(5)
	v_lshlrev_b32_e32 v128, 16, v0
	v_and_b32_e32 v129, 0xffff0000, v0
	v_lshlrev_b32_e32 v0, 16, v1
	v_and_b32_e32 v1, 0xffff0000, v1
	s_waitcnt vmcnt(4)
	v_lshlrev_b32_e32 v136, 16, v4
	v_and_b32_e32 v137, 0xffff0000, v4
	v_lshlrev_b32_e32 v138, 16, v5
	v_and_b32_e32 v139, 0xffff0000, v5
	s_waitcnt vmcnt(2)
	v_lshlrev_b32_e32 v4, 16, v12
	v_and_b32_e32 v5, 0xffff0000, v12
	v_xor_b32_e32 v147, 0x80000000, v129
	v_xor_b32_e32 v146, 0x80000000, v128
	v_lshlrev_b32_e32 v140, 16, v8
	v_and_b32_e32 v141, 0xffff0000, v8
	v_lshlrev_b32_e32 v142, 16, v9
	v_and_b32_e32 v143, 0xffff0000, v9
	v_lshlrev_b32_e32 v8, 16, v13
	v_and_b32_e32 v9, 0xffff0000, v13
	v_pk_fma_f32 v[4:5], v[72:73], v[4:5], v[146:147] op_sel_hi:[0,1,1]
	v_xor_b32_e32 v147, 0x80000000, v1
	v_xor_b32_e32 v146, 0x80000000, v0
	v_pk_fma_f32 v[8:9], v[72:73], v[8:9], v[146:147] op_sel_hi:[0,1,1]
	s_waitcnt vmcnt(1)
	v_lshlrev_b32_e32 v12, 16, v16
	v_and_b32_e32 v13, 0xffff0000, v16
	v_lshlrev_b32_e32 v16, 16, v17
	v_and_b32_e32 v17, 0xffff0000, v17
	s_waitcnt lgkmcnt(3)
	v_pk_fma_f32 v[0:1], v[56:57], v[8:9], v[0:1]
	v_xor_b32_e32 v9, 0x80000000, v139
	v_xor_b32_e32 v8, 0x80000000, v138
	v_pk_fma_f32 v[16:17], v[72:73], v[16:17], v[8:9] op_sel_hi:[0,1,1]
	v_xor_b32_e32 v9, 0x80000000, v137
	v_xor_b32_e32 v8, 0x80000000, v136
	s_waitcnt vmcnt(0)
	v_lshlrev_b32_e32 v144, 16, v20
	v_and_b32_e32 v145, 0xffff0000, v20
	v_lshlrev_b32_e32 v20, 16, v21
	v_and_b32_e32 v21, 0xffff0000, v21
	v_pk_fma_f32 v[4:5], v[54:55], v[4:5], v[128:129]
	v_pk_fma_f32 v[8:9], v[72:73], v[12:13], v[8:9] op_sel_hi:[0,1,1]
	s_waitcnt lgkmcnt(1)
	v_pk_fma_f32 v[12:13], v[60:61], v[16:17], v[138:139]
	v_xor_b32_e32 v17, 0x80000000, v141
	v_xor_b32_e32 v16, 0x80000000, v140
	v_xor_b32_e32 v55, 0x80000000, v143
	v_xor_b32_e32 v54, 0x80000000, v142
	v_pk_fma_f32 v[16:17], v[72:73], v[144:145], v[16:17] op_sel_hi:[0,1,1]
	v_pk_fma_f32 v[20:21], v[72:73], v[20:21], v[54:55] op_sel_hi:[0,1,1]
	v_lshlrev_b32_e32 v128, 16, v2
	v_and_b32_e32 v129, 0xffff0000, v2
	s_waitcnt lgkmcnt(0)
	v_pk_fma_f32 v[54:55], v[134:135], v[20:21], v[142:143]
	v_pk_fma_f32 v[56:57], v[132:133], v[16:17], v[140:141]
	v_lshlrev_b32_e32 v2, 16, v3
	v_and_b32_e32 v3, 0xffff0000, v3
	v_lshlrev_b32_e32 v140, 16, v6
	v_and_b32_e32 v141, 0xffff0000, v6
	v_lshlrev_b32_e32 v142, 16, v7
	v_and_b32_e32 v143, 0xffff0000, v7
	v_lshlrev_b32_e32 v6, 16, v14
	v_and_b32_e32 v7, 0xffff0000, v14
	v_xor_b32_e32 v151, 0x80000000, v129
	v_xor_b32_e32 v150, 0x80000000, v128
	v_lshlrev_b32_e32 v144, 16, v10
	v_and_b32_e32 v145, 0xffff0000, v10
	v_lshlrev_b32_e32 v146, 16, v11
	v_and_b32_e32 v147, 0xffff0000, v11
	v_lshlrev_b32_e32 v10, 16, v15
	v_and_b32_e32 v11, 0xffff0000, v15
	v_pk_fma_f32 v[6:7], v[72:73], v[6:7], v[150:151] op_sel_hi:[0,1,1]
	v_xor_b32_e32 v151, 0x80000000, v3
	v_xor_b32_e32 v150, 0x80000000, v2
	v_pk_fma_f32 v[8:9], v[58:59], v[8:9], v[136:137]
	ds_read_b128 v[58:61], v223 offset:39040
	ds_read_b128 v[132:135], v223 offset:34960
	ds_read_b128 v[136:139], v223 offset:37008
	v_pk_fma_f32 v[10:11], v[72:73], v[10:11], v[150:151] op_sel_hi:[0,1,1]
	v_lshlrev_b32_e32 v14, 16, v18
	v_and_b32_e32 v15, 0xffff0000, v18
	v_lshlrev_b32_e32 v18, 16, v19
	v_and_b32_e32 v19, 0xffff0000, v19
	v_pk_fma_f32 v[2:3], v[26:27], v[10:11], v[2:3]
	v_xor_b32_e32 v11, 0x80000000, v143
	v_xor_b32_e32 v10, 0x80000000, v142
	v_pk_fma_f32 v[18:19], v[72:73], v[18:19], v[10:11] op_sel_hi:[0,1,1]
	v_xor_b32_e32 v11, 0x80000000, v141
	v_xor_b32_e32 v10, 0x80000000, v140
	v_pk_fma_f32 v[10:11], v[72:73], v[14:15], v[10:11] op_sel_hi:[0,1,1]
	s_waitcnt lgkmcnt(1)
	v_pk_fma_f32 v[10:11], v[132:133], v[10:11], v[140:141]
	v_pk_fma_f32 v[14:15], v[134:135], v[18:19], v[142:143]
	ds_read_b128 v[132:135], v223 offset:39056
	v_pk_mul_f32 v[20:21], v[58:59], v[8:9]
	v_pk_mul_f32 v[16:17], v[60:61], v[12:13]
	v_mul_f32_e32 v58, v20, v20
	v_pk_fma_f32 v[58:59], v[20:21], v[20:21], v[58:59] op_sel_hi:[1,1,0]
	v_lshlrev_b32_e32 v148, 16, v22
	v_and_b32_e32 v149, 0xffff0000, v22
	v_lshlrev_b32_e32 v22, 16, v23
	v_and_b32_e32 v23, 0xffff0000, v23
	v_pk_fma_f32 v[6:7], v[24:25], v[6:7], v[128:129]
	v_xor_b32_e32 v19, 0x80000000, v145
	v_xor_b32_e32 v18, 0x80000000, v144
	v_xor_b32_e32 v25, 0x80000000, v147
	v_xor_b32_e32 v24, 0x80000000, v146
	v_mul_f32_e32 v58, v16, v16
	v_pk_fma_f32 v[18:19], v[72:73], v[148:149], v[18:19] op_sel_hi:[0,1,1]
	v_pk_fma_f32 v[22:23], v[72:73], v[22:23], v[24:25] op_sel_hi:[0,1,1]
	v_pk_fma_f32 v[60:61], v[16:17], v[16:17], v[58:59] op_sel_hi:[1,1,0]
	s_waitcnt lgkmcnt(1)
	v_pk_fma_f32 v[24:25], v[138:139], v[22:23], v[146:147]
	v_pk_fma_f32 v[26:27], v[136:137], v[18:19], v[144:145]
	s_waitcnt lgkmcnt(0)
	v_pk_mul_f32 v[18:19], v[134:135], v[14:15]
	v_pk_mul_f32 v[22:23], v[132:133], v[10:11]
	v_mul_f32_e32 v58, v18, v18
	v_mul_f32_e32 v88, v22, v22
	v_mul_f32_e32 v126, v23, v23
	v_mul_f32_e32 v60, v19, v19
	v_pk_add_f32 v[72:73], v[88:89], v[126:127]
	v_pk_add_f32 v[58:59], v[58:59], v[60:61]
	v_lshl_add_u64 v[60:61], v[78:79], 0, s[6:7]
	v_pk_add_f32 v[58:59], v[72:73], v[58:59]
	v_cvt_pk_bf16_f32 v56, v56, v57
	v_add_f32_e32 v72, v58, v59
	v_cvt_pk_bf16_f32 v57, v54, v55
	v_cvt_pk_bf16_f32 v58, v26, v27
	v_cvt_pk_bf16_f32 v59, v24, v25
	global_store_dwordx4 v[60:61], v[56:59], off
	s_nop 1
	s_mov_b64 s[6:7], 0x240
	v_cvt_pk_bf16_f32 v24, v4, v5
	v_lshl_add_u64 v[54:55], v[78:79], 0, s[6:7]
	v_cvt_pk_bf16_f32 v25, v0, v1
	v_cvt_pk_bf16_f32 v26, v6, v7
	v_cvt_pk_bf16_f32 v27, v2, v3
	global_store_dwordx4 v[54:55], v[24:27], off
	s_nop 1
	v_cvt_pk_bf16_f32 v24, v44, v45
	v_lshl_add_u64 v[54:55], v[78:79], 0, 64
	v_cvt_pk_bf16_f32 v25, v46, v47
	v_cvt_pk_bf16_f32 v26, v50, v51
	v_cvt_pk_bf16_f32 v27, v52, v53
	global_store_dwordx4 v[54:55], v[24:27], off
	s_nop 1
	s_mov_b32 s6, 0xf800000
	v_pk_add_f32 v[60:61], v[42:43], -1.0 op_sel_hi:[1,0]
	s_waitcnt lgkmcnt(0)
	v_mov_b32_e32 v24, v72
	s_nop 1
	v_permlane16_swap_b32_e32 v72, v24
	v_add_f32_e32 v24, v72, v24
	v_mov_b32_e32 v25, v24
	s_nop 1
	v_permlane32_swap_b32_e32 v24, v25
	v_add_f32_e32 v24, v24, v25
	v_cmp_gt_f32_e32 vcc, s6, v24
	v_mul_f32_e32 v25, 0x4f800000, v24
	v_pk_add_f32 v[72:73], v[40:41], -1.0 op_sel_hi:[1,0]
	v_cndmask_b32_e32 v24, v24, v25, vcc
	v_sqrt_f32_e32 v25, v24
	s_nop 0
	v_add_u32_e32 v26, -1, v25
	v_fma_f32 v27, -v26, v25, v24
	v_cmp_ge_f32_e64 s[46:47], 0, v27
	v_add_u32_e32 v27, 1, v25
	s_nop 0
	v_cndmask_b32_e64 v26, v25, v26, s[46:47]
	v_fma_f32 v25, -v27, v25, v24
	v_cmp_lt_f32_e64 s[46:47], 0, v25
	s_nop 1
	v_cndmask_b32_e64 v25, v26, v27, s[46:47]
	v_mul_f32_e32 v26, 0x37800000, v25
	v_cndmask_b32_e32 v25, v25, v26, vcc
	v_cmp_class_f32_e32 vcc, v24, v207
	s_nop 1
	v_cndmask_b32_e32 v24, v25, v24, vcc
	v_max_f32_e32 v24, 0x2b8cbccc, v24
	v_div_scale_f32 v25, s[6:7], v24, v24, 1.0
	v_rcp_f32_e32 v26, v25
	s_mov_b64 s[6:7], 0x180
	v_fma_f32 v27, -v25, v26, 1.0
	v_fmac_f32_e32 v26, v27, v26
	v_div_scale_f32 v27, vcc, 1.0, v24, 1.0
	v_mul_f32_e32 v44, v27, v26
	v_fma_f32 v45, -v25, v44, v27
	v_fmac_f32_e32 v44, v45, v26
	v_fma_f32 v25, -v25, v44, v27
	v_div_fmas_f32 v25, v25, v26, v44
	v_div_fixup_f32 v54, v25, v24, 1.0
	ds_read_b128 v[24:27], v223 offset:40960
	ds_read_b128 v[44:47], v223 offset:40976
	ds_read_b128 v[50:53], v223 offset:43008
	v_pk_mul_f32 v[56:57], v[74:75], v[54:55] op_sel_hi:[1,0]
	v_pk_mul_f32 v[58:59], v[76:77], v[54:55] op_sel_hi:[1,0]
	s_waitcnt lgkmcnt(2)
	v_pk_fma_f32 v[24:25], v[72:73], v[24:25], 1.0 op_sel_hi:[1,1,0]
	v_pk_fma_f32 v[26:27], v[60:61], v[26:27], 1.0 op_sel_hi:[1,1,0]
	v_pk_mul_f32 v[42:43], v[42:43], v[58:59]
	v_pk_mul_f32 v[60:61], v[68:69], v[26:27]
	v_pk_mul_f32 v[68:69], v[70:71], v[24:25]
	v_pk_mul_f32 v[26:27], v[62:63], v[60:61]
	v_pk_mul_f32 v[24:25], v[64:65], v[68:69]
	s_waitcnt lgkmcnt(0)
	v_pk_mul_f32 v[26:27], v[52:53], v[26:27]
	v_pk_mul_f32 v[24:25], v[50:51], v[24:25]
	v_xor_b32_e32 v62, 0x80000000, v59
	v_add_f32_e32 v24, v24, v25
	v_add_f32_e32 v25, v26, v27
	v_add_f32_e32 v24, v24, v25
	v_add_f32_e32 v55, 0, v24
	ds_read_b128 v[24:27], v223 offset:43024
	v_xor_b32_e32 v63, 0x80000000, v58
	v_xor_b32_e32 v64, 0x80000000, v57
	v_xor_b32_e32 v65, 0x80000000, v56
	v_pk_mul_f32 v[40:41], v[40:41], v[56:57]
	v_pk_add_f32 v[56:57], v[38:39], -1.0 op_sel_hi:[1,0]
	v_pk_add_f32 v[58:59], v[36:37], -1.0 op_sel_hi:[1,0]
	v_pk_fma_f32 v[46:47], v[56:57], v[46:47], 1.0 op_sel_hi:[1,1,0]
	v_pk_fma_f32 v[44:45], v[58:59], v[44:45], 1.0 op_sel_hi:[1,1,0]
	v_pk_mul_f32 v[46:47], v[84:85], v[46:47]
	v_pk_mul_f32 v[44:45], v[86:87], v[44:45]
	v_pk_mul_f32 v[58:59], v[80:81], v[46:47]
	v_pk_mul_f32 v[56:57], v[82:83], v[44:45]
	s_waitcnt lgkmcnt(0)
	v_pk_mul_f32 v[26:27], v[26:27], v[58:59]
	v_pk_mul_f32 v[24:25], v[24:25], v[56:57]
	v_pk_mul_f32 v[50:51], v[90:91], v[54:55] op_sel_hi:[1,0]
	v_add_f32_e32 v24, v24, v25
	v_add_f32_e32 v25, v26, v27
	v_pk_mul_f32 v[52:53], v[92:93], v[54:55] op_sel_hi:[1,0]
	v_add_f32_e32 v24, v24, v25
	v_add_f32_e32 v55, v55, v24
	v_xor_b32_e32 v56, 0x80000000, v53
	v_xor_b32_e32 v57, 0x80000000, v52
	v_xor_b32_e32 v58, 0x80000000, v51
	v_xor_b32_e32 v59, 0x80000000, v50
	v_pk_mul_f32 v[36:37], v[36:37], v[50:51]
	v_lshl_add_u64 v[50:51], v[78:79], 0, s[30:31]
	v_cvt_pk_bf16_f32 v24, v68, v69
	v_cvt_pk_bf16_f32 v25, v60, v61
	v_cvt_pk_bf16_f32 v26, v44, v45
	v_cvt_pk_bf16_f32 v27, v46, v47
	global_store_dwordx4 v[50:51], v[24:27], off
	s_nop 1
	v_pk_mul_f32 v[38:39], v[38:39], v[52:53]
	v_lshl_add_u64 v[44:45], v[78:79], 0, s[34:35]
	v_cvt_pk_bf16_f32 v24, v65, v64
	v_cvt_pk_bf16_f32 v25, v63, v62
	v_cvt_pk_bf16_f32 v26, v59, v58
	v_cvt_pk_bf16_f32 v27, v57, v56
	global_store_dwordx4 v[44:45], v[24:27], off
	s_nop 1
	v_lshl_add_u64 v[44:45], v[78:79], 0, s[6:7]
	v_cvt_pk_bf16_f32 v24, v40, v41
	v_cvt_pk_bf16_f32 v25, v42, v43
	v_cvt_pk_bf16_f32 v26, v36, v37
	v_cvt_pk_bf16_f32 v27, v38, v39
	global_store_dwordx4 v[44:45], v[24:27], off
	s_nop 1
	ds_read_b128 v[24:27], v223 offset:41088
	ds_read_b128 v[36:39], v223 offset:41104
	ds_read_b128 v[40:43], v223 offset:43136
	v_pk_add_f32 v[44:45], v[34:35], -1.0 op_sel_hi:[1,0]
	v_pk_add_f32 v[46:47], v[32:33], -1.0 op_sel_hi:[1,0]
	s_waitcnt lgkmcnt(2)
	v_pk_fma_f32 v[26:27], v[44:45], v[26:27], 1.0 op_sel_hi:[1,1,0]
	v_pk_fma_f32 v[24:25], v[46:47], v[24:25], 1.0 op_sel_hi:[1,1,0]
	v_pk_mul_f32 v[12:13], v[12:13], v[26:27]
	v_pk_mul_f32 v[8:9], v[8:9], v[24:25]
	v_pk_mul_f32 v[0:1], v[0:1], v[12:13]
	v_pk_mul_f32 v[4:5], v[4:5], v[8:9]
	s_waitcnt lgkmcnt(0)
	v_pk_mul_f32 v[0:1], v[42:43], v[0:1]
	v_pk_mul_f32 v[4:5], v[40:41], v[4:5]
	v_add_f32_e32 v0, v0, v1
	v_add_f32_e32 v4, v4, v5
	v_pk_mul_f32 v[16:17], v[16:17], v[54:55] op_sel_hi:[1,0]
	v_add_f32_e32 v0, v4, v0
	v_add_f32_e32 v40, v55, v0
	v_xor_b32_e32 v41, 0x80000000, v17
	v_xor_b32_e32 v42, 0x80000000, v16
	v_pk_mul_f32 v[4:5], v[34:35], v[16:17]
	v_pk_mul_f32 v[0:1], v[22:23], v[54:55] op_sel_hi:[1,0]
	v_pk_mul_f32 v[22:23], v[18:19], v[54:55] op_sel_hi:[1,0]
	ds_read_b128 v[16:19], v223 offset:43152
	v_pk_add_f32 v[24:25], v[30:31], -1.0 op_sel_hi:[1,0]
	v_pk_add_f32 v[26:27], v[28:29], -1.0 op_sel_hi:[1,0]
	v_pk_fma_f32 v[24:25], v[24:25], v[38:39], 1.0 op_sel_hi:[1,1,0]
	v_pk_fma_f32 v[26:27], v[26:27], v[36:37], 1.0 op_sel_hi:[1,1,0]
	v_pk_mul_f32 v[14:15], v[14:15], v[24:25]
	v_pk_mul_f32 v[10:11], v[10:11], v[26:27]
	v_pk_mul_f32 v[2:3], v[2:3], v[14:15]
	v_pk_mul_f32 v[6:7], v[6:7], v[10:11]
	s_waitcnt lgkmcnt(0)
	v_pk_mul_f32 v[2:3], v[18:19], v[2:3]
	v_pk_mul_f32 v[6:7], v[16:17], v[6:7]
	v_pk_mul_f32 v[20:21], v[20:21], v[54:55] op_sel_hi:[1,0]
	v_add_f32_e32 v6, v6, v7
	v_add_f32_e32 v2, v2, v3
	v_xor_b32_e32 v43, 0x80000000, v21
	v_xor_b32_e32 v44, 0x80000000, v20
	v_pk_mul_f32 v[20:21], v[32:33], v[20:21]
	v_add_f32_e32 v2, v6, v2
	v_xor_b32_e32 v32, 0x80000000, v0
	v_pk_mul_f32 v[16:17], v[28:29], v[0:1]
	s_mov_b64 s[6:7], 0xc0
	v_cvt_pk_bf16_f32 v0, v8, v9
	v_add_f32_e32 v24, v40, v2
	v_xor_b32_e32 v25, 0x80000000, v23
	v_xor_b32_e32 v26, 0x80000000, v22
	v_xor_b32_e32 v27, 0x80000000, v1
	v_lshl_add_u64 v[18:19], v[78:79], 0, s[6:7]
	v_cvt_pk_bf16_f32 v1, v12, v13
	v_cvt_pk_bf16_f32 v2, v10, v11
	v_cvt_pk_bf16_f32 v3, v14, v15
	global_store_dwordx4 v[18:19], v[0:3], off
	s_nop 1
	s_mov_b64 s[6:7], 0x140
	v_cvt_pk_bf16_f32 v0, v44, v43
	v_pk_mul_f32 v[6:7], v[30:31], v[22:23]
	v_lshl_add_u64 v[8:9], v[78:79], 0, s[6:7]
	v_cvt_pk_bf16_f32 v1, v42, v41
	v_cvt_pk_bf16_f32 v2, v32, v27
	v_cvt_pk_bf16_f32 v3, v26, v25
	global_store_dwordx4 v[8:9], v[0:3], off
	s_nop 1
	s_mov_b64 s[6:7], 0x1c0
	v_cvt_pk_bf16_f32 v0, v20, v21
	v_lshl_add_u64 v[8:9], v[78:79], 0, s[6:7]
	v_cvt_pk_bf16_f32 v1, v4, v5
	v_cvt_pk_bf16_f32 v2, v16, v17
	v_cvt_pk_bf16_f32 v3, v6, v7
	global_store_dwordx4 v[8:9], v[0:3], off
	s_nop 1
	ds_bpermute_b32 v0, v131, v24
	s_waitcnt lgkmcnt(0)
	v_add_f32_e32 v0, v24, v0
	v_mov_b32_e32 v1, v0
	s_nop 1
	v_permlane32_swap_b32_e32 v0, v1
	s_and_saveexec_b64 s[46:47], s[44:45]
	s_cbranch_execz .LBB0_901
	v_add_f32_e32 v2, v0, v1
	v_lshlrev_b64 v[0:1], 5, v[66:67]
	v_lshl_add_u64 v[0:1], s[58:59], 0, v[0:1]
	global_store_dword v[0:1], v2, off
	s_branch .LBB0_901
